# attention row-max: max over raw scores then one multiply instead of scaling every score before the max (bit-identical; 132 VALU instructions fewer in 3 blocks)
# speedup vs baseline: 1.0011x; 1.0011x over previous
.LBB0_482:
	s_ashr_i32 s87, s86, 31
	s_lshl_b64 s[86:87], s[86:87], 2
	s_add_u32 s86, s50, s86
	s_addc_u32 s87, s51, s87
	global_load_dword v0, v145, s[86:87]
	s_cmp_lg_u32 s19, 0
	s_cselect_b64 s[86:87], -1, 0
	s_mov_b32 s81, s85
	s_and_b64 vcc, exec, s[86:87]
	v_mbcnt_hi_u32_b32 v180, -1, v183
	s_waitcnt vmcnt(0)
	v_mul_f32_e32 v179, 0x3fb8aa3b, v0
	s_cbranch_vccz .LBB0_487
	ds_read_b128 v[0:3], v176
	ds_read_b128 v[4:7], v176 offset:32
	v_add_u32_e32 v153, s17, v159
	v_add_u32_e32 v182, 0x9b, v153
	s_waitcnt lgkmcnt(1)
	v_mfma_f32_32x32x16_bf16 v[64:79], v[0:3], v[140:143], 0
	ds_read_b128 v[0:3], v176 offset:64
	ds_read_b128 v[48:51], v176 offset:13856
	ds_read_b128 v[184:187], v176 offset:18464
	s_waitcnt lgkmcnt(3)
	v_mfma_f32_32x32x16_bf16 v[64:79], v[4:7], v[136:139], v[64:79]
	s_waitcnt lgkmcnt(2)
	v_mfma_f32_32x32x16_bf16 v[64:79], v[0:3], v[132:135], v[64:79]
	ds_read_b128 v[0:3], v176 offset:96
	s_waitcnt lgkmcnt(0)
	v_mfma_f32_32x32x16_bf16 v[64:79], v[0:3], v[128:131], v[64:79]
	ds_read_b128 v[0:3], v176 offset:4608
	s_waitcnt lgkmcnt(0)
	v_mfma_f32_32x32x16_bf16 v[32:47], v[0:3], v[140:143], 0
	ds_read_b128 v[0:3], v176 offset:4640
	s_nop 7
	v_mul_f32_e32 v64, 0x3e38aa3b, v64
	v_mul_f32_e32 v65, 0x3e38aa3b, v65
	v_mul_f32_e32 v66, 0x3e38aa3b, v66
	v_mul_f32_e32 v67, 0x3e38aa3b, v67
	v_mul_f32_e32 v68, 0x3e38aa3b, v68
	v_mul_f32_e32 v69, 0x3e38aa3b, v69
	s_waitcnt lgkmcnt(0)
	v_mfma_f32_32x32x16_bf16 v[32:47], v[0:3], v[136:139], v[32:47]
	ds_read_b128 v[0:3], v176 offset:4672
	v_mul_f32_e32 v70, 0x3e38aa3b, v70
	v_mul_f32_e32 v71, 0x3e38aa3b, v71
	v_mul_f32_e32 v72, 0x3e38aa3b, v72
	v_mul_f32_e32 v73, 0x3e38aa3b, v73
	v_mul_f32_e32 v74, 0x3e38aa3b, v74
	v_mul_f32_e32 v75, 0x3e38aa3b, v75
	s_waitcnt lgkmcnt(0)
	v_mfma_f32_32x32x16_bf16 v[32:47], v[0:3], v[132:135], v[32:47]
	ds_read_b128 v[0:3], v176 offset:4704
	v_mul_f32_e32 v76, 0x3e38aa3b, v76
	v_mul_f32_e32 v77, 0x3e38aa3b, v77
	v_mul_f32_e32 v78, 0x3e38aa3b, v78
	v_mul_f32_e32 v79, 0x3e38aa3b, v79
	s_waitcnt lgkmcnt(0)
	v_mfma_f32_32x32x16_bf16 v[32:47], v[0:3], v[128:131], v[32:47]
	ds_read_b128 v[0:3], v176 offset:9216
	s_waitcnt lgkmcnt(0)
	v_mfma_f32_32x32x16_bf16 v[16:31], v[0:3], v[140:143], 0
	ds_read_b128 v[0:3], v176 offset:9248
	s_waitcnt lgkmcnt(0)
	v_mfma_f32_32x32x16_bf16 v[16:31], v[0:3], v[136:139], v[16:31]
	ds_read_b128 v[0:3], v176 offset:9280
	s_waitcnt lgkmcnt(0)
	v_mfma_f32_32x32x16_bf16 v[16:31], v[0:3], v[132:135], v[16:31]
	ds_read_b128 v[0:3], v176 offset:9312
	s_waitcnt lgkmcnt(0)
	v_mfma_f32_32x32x16_bf16 v[16:31], v[0:3], v[128:131], v[16:31]
	ds_read_b128 v[0:3], v176 offset:13824
	s_waitcnt lgkmcnt(0)
	v_mfma_f32_32x32x16_bf16 v[0:15], v[0:3], v[140:143], 0
	v_mfma_f32_32x32x16_bf16 v[0:15], v[48:51], v[136:139], v[0:15]
	ds_read_b128 v[48:51], v176 offset:13888
	s_waitcnt lgkmcnt(0)
	v_mfma_f32_32x32x16_bf16 v[0:15], v[48:51], v[132:135], v[0:15]
	ds_read_b128 v[48:51], v176 offset:13920
	s_waitcnt lgkmcnt(0)
	v_mfma_f32_32x32x16_bf16 v[0:15], v[48:51], v[128:131], v[0:15]
	ds_read_b128 v[48:51], v176 offset:18432
	s_waitcnt lgkmcnt(0)
	v_mfma_f32_32x32x16_bf16 v[48:63], v[48:51], v[140:143], 0
	v_mfma_f32_32x32x16_bf16 v[48:63], v[184:187], v[136:139], v[48:63]
	ds_read_b128 v[184:187], v176 offset:18496
	s_waitcnt lgkmcnt(0)
	v_mfma_f32_32x32x16_bf16 v[48:63], v[184:187], v[132:135], v[48:63]
	ds_read_b128 v[184:187], v176 offset:18528
	s_waitcnt lgkmcnt(0)
	v_mfma_f32_32x32x16_bf16 v[48:63], v[184:187], v[128:131], v[48:63]
	v_or_b32_e32 v184, s18, v158
	v_sub_u32_e32 v185, v184, v153
	v_cmp_gt_i32_e32 vcc, s92, v185
	v_sub_u32_e32 v186, v153, v184
	v_mul_f32_e32 v187, 0x3e38aa3b, v33
	v_cndmask_b32_e32 v64, v177, v64, vcc
	v_cmp_lt_i32_e32 vcc, s93, v186
	s_nop 4
	v_mul_f32_e32 v48, 0x3e38aa3b, v48
	v_mul_f32_e32 v49, 0x3e38aa3b, v49
	v_cndmask_b32_e32 v65, v177, v65, vcc
	v_cmp_gt_i32_e32 vcc, s4, v185
	v_max3_f32 v186, v64, s1, v65
	v_mul_f32_e32 v50, 0x3e38aa3b, v50
	v_cndmask_b32_e32 v66, v177, v66, vcc
	v_cmp_gt_i32_e32 vcc, s5, v185
	v_mul_f32_e32 v51, 0x3e38aa3b, v51
	v_mul_f32_e32 v52, 0x3e38aa3b, v52
	v_cndmask_b32_e32 v67, v177, v67, vcc
	v_cmp_gt_i32_e32 vcc, s6, v185
	v_max3_f32 v186, v186, v66, v67
	v_mul_f32_e32 v53, 0x3e38aa3b, v53
	v_cndmask_b32_e32 v68, v177, v68, vcc
	v_cmp_gt_i32_e32 vcc, s7, v185
	s_nop 1
	v_cndmask_b32_e32 v69, v177, v69, vcc
	v_cmp_gt_i32_e32 vcc, s8, v185
	v_max3_f32 v186, v186, v68, v69
	s_nop 0
	v_cndmask_b32_e32 v70, v177, v70, vcc
	v_cmp_gt_i32_e32 vcc, s9, v185
	s_nop 1
	v_cndmask_b32_e32 v71, v177, v71, vcc
	v_cmp_gt_i32_e32 vcc, s33, v185
	v_max3_f32 v186, v186, v70, v71
	s_nop 0
	v_cndmask_b32_e32 v72, v177, v72, vcc
	v_cmp_gt_i32_e32 vcc, s10, v185
	s_nop 1
	v_cndmask_b32_e32 v73, v177, v73, vcc
	v_cmp_gt_i32_e32 vcc, s11, v185
	v_max3_f32 v186, v186, v72, v73
	s_nop 0
	v_cndmask_b32_e32 v74, v177, v74, vcc
	v_cmp_gt_i32_e32 vcc, s12, v185
	s_nop 1
	v_cndmask_b32_e32 v75, v177, v75, vcc
	v_cmp_gt_i32_e32 vcc, s13, v185
	v_max3_f32 v186, v186, v74, v75
	s_nop 0
	v_cndmask_b32_e32 v76, v177, v76, vcc
	v_cmp_gt_i32_e32 vcc, s14, v185
	s_nop 1
	v_cndmask_b32_e32 v77, v177, v77, vcc
	v_cmp_gt_i32_e32 vcc, s15, v185
	v_max3_f32 v186, v186, v76, v77
	s_nop 0
	v_cndmask_b32_e32 v78, v177, v78, vcc
	v_cmp_gt_i32_e32 vcc, s97, v185
	s_nop 1
	v_cndmask_b32_e32 v79, v177, v79, vcc
	v_max3_f32 v185, v186, v78, v79
	v_mul_f32_e32 v186, 0x3e38aa3b, v32
	v_max3_f32 v185, v185, v186, v187
	v_max_f32_e32 v186, v34, v35
	v_max3_f32 v186, v186, v36, v37
	v_max3_f32 v186, v186, v38, v39
	v_max3_f32 v186, v186, v40, v41
	v_max3_f32 v186, v186, v42, v43
	v_max3_f32 v186, v186, v44, v45
	v_max3_f32 v186, v186, v46, v47
	v_max3_f32 v186, v186, v16, v17
	v_max3_f32 v186, v186, v18, v19
	v_max3_f32 v186, v186, v20, v21
	v_max3_f32 v186, v186, v22, v23
	v_max3_f32 v186, v186, v24, v25
	v_max3_f32 v186, v186, v26, v27
	v_max3_f32 v186, v186, v28, v29
	v_max3_f32 v186, v186, v30, v31
	v_max3_f32 v186, v186, v0, v1
	v_max3_f32 v186, v186, v2, v3
	v_max3_f32 v186, v186, v4, v5
	v_max3_f32 v186, v186, v6, v7
	v_max3_f32 v186, v186, v8, v9
	v_max3_f32 v186, v186, v10, v11
	v_max3_f32 v186, v186, v12, v13
	v_max3_f32 v186, v186, v14, v15
	v_mul_f32_e32 v186, 0x3e38aa3b, v186
	v_max_f32_e32 v185, v185, v186
	v_add_u32_e32 v186, 0x80, v153
	v_cmp_ge_u32_e32 vcc, v184, v186
	v_add_u32_e32 v186, 0x81, v153
	s_nop 0
	v_cndmask_b32_e32 v48, v177, v48, vcc
	v_cmp_ge_u32_e32 vcc, v184, v186
	v_add_u32_e32 v186, 0x82, v153
	s_nop 0
	v_cndmask_b32_e32 v49, v177, v49, vcc
	v_cmp_ge_u32_e32 vcc, v184, v186
	v_add_u32_e32 v186, 0x83, v153
	v_max3_f32 v185, v185, v48, v49
	v_cndmask_b32_e32 v50, v177, v50, vcc
	v_cmp_ge_u32_e32 vcc, v184, v186
	s_nop 1
	v_cndmask_b32_e32 v217, v177, v51, vcc
	v_max3_f32 v51, v185, v50, v217
	v_add_u32_e32 v185, 0x88, v153
	v_cmp_ge_u32_e32 vcc, v184, v185
	s_nop 1
	v_cndmask_b32_e32 v218, v177, v52, vcc
	v_add_u32_e32 v52, 0x89, v153
	v_cmp_ge_u32_e32 vcc, v184, v52
	v_add_u32_e32 v52, 0x8a, v153
	s_nop 0
	v_cndmask_b32_e32 v219, v177, v53, vcc
	v_mul_f32_e32 v53, 0x3e38aa3b, v54
	v_cmp_ge_u32_e32 vcc, v184, v52
	v_add_u32_e32 v52, 0x8b, v153
	v_max3_f32 v51, v51, v218, v219
	v_cndmask_b32_e32 v220, v177, v53, vcc
	v_mul_f32_e32 v53, 0x3e38aa3b, v55
	v_cmp_ge_u32_e32 vcc, v184, v52
	v_add_u32_e32 v52, 0x90, v153
	s_nop 0
	v_cndmask_b32_e32 v221, v177, v53, vcc
	v_mul_f32_e32 v53, 0x3e38aa3b, v56
	v_cmp_ge_u32_e32 vcc, v184, v52
	v_add_u32_e32 v52, 0x91, v153
	v_max3_f32 v51, v51, v220, v221
	v_cndmask_b32_e32 v222, v177, v53, vcc
	v_mul_f32_e32 v53, 0x3e38aa3b, v57
	v_cmp_ge_u32_e32 vcc, v184, v52
	v_add_u32_e32 v52, 0x92, v153
	s_nop 0
	v_cndmask_b32_e32 v223, v177, v53, vcc
	v_mul_f32_e32 v53, 0x3e38aa3b, v58
	v_cmp_ge_u32_e32 vcc, v184, v52
	v_add_u32_e32 v52, 0x93, v153
	v_max3_f32 v51, v51, v222, v223
	v_cndmask_b32_e32 v224, v177, v53, vcc
	v_mul_f32_e32 v53, 0x3e38aa3b, v59
	v_cmp_ge_u32_e32 vcc, v184, v52
	v_add_u32_e32 v52, 0x98, v153
	s_nop 0
	v_cndmask_b32_e32 v225, v177, v53, vcc
	v_mul_f32_e32 v53, 0x3e38aa3b, v60
	v_cmp_ge_u32_e32 vcc, v184, v52
	v_add_u32_e32 v52, 0x99, v153
	v_max3_f32 v51, v51, v224, v225
	v_cndmask_b32_e32 v226, v177, v53, vcc
	v_mul_f32_e32 v53, 0x3e38aa3b, v61
	v_cmp_ge_u32_e32 vcc, v184, v52
	v_add_u32_e32 v52, 0x9a, v153
	s_nop 0
	v_cndmask_b32_e32 v227, v177, v53, vcc
	v_mul_f32_e32 v53, 0x3e38aa3b, v62
	v_cmp_ge_u32_e32 vcc, v184, v52
	v_mul_f32_e32 v52, 0x3e38aa3b, v63
	v_max3_f32 v51, v51, v226, v227
	v_cndmask_b32_e32 v228, v177, v53, vcc
	v_cmp_ge_u32_e32 vcc, v184, v182
	v_and_b32_e32 v53, 64, v180
	v_add_u32_e32 v53, 64, v53
	v_cndmask_b32_e32 v229, v177, v52, vcc
	v_xor_b32_e32 v52, 32, v180
	v_cmp_lt_i32_e32 vcc, v52, v53
	v_max3_f32 v51, v51, v228, v229
	s_nop 0
	v_cndmask_b32_e32 v52, v180, v52, vcc
	v_lshlrev_b32_e32 v230, 2, v52
	ds_bpermute_b32 v52, v230, v51
	s_waitcnt lgkmcnt(0)
	v_max3_f32 v231, v51, v52, v179
	v_sub_f32_e32 v51, v64, v231
	v_exp_f32_e32 v203, v51
	v_sub_f32_e32 v52, v65, v231
	v_exp_f32_e32 v206, v52
	v_sub_f32_e32 v52, v66, v231
	v_exp_f32_e32 v211, v52
	v_sub_f32_e32 v52, v67, v231
	v_exp_f32_e32 v212, v52
	v_sub_f32_e32 v52, v68, v231
	v_add_f32_e32 v51, 0, v203
	v_exp_f32_e32 v213, v52
	v_sub_f32_e32 v52, v69, v231
	v_add_f32_e32 v51, v206, v51
	v_exp_f32_e32 v214, v52
	v_sub_f32_e32 v52, v70, v231
	v_add_f32_e32 v51, v211, v51
	v_exp_f32_e32 v215, v52
	v_sub_f32_e32 v52, v71, v231
	v_add_f32_e32 v51, v212, v51
	v_exp_f32_e32 v216, v52
	v_sub_f32_e32 v52, v72, v231
	v_add_f32_e32 v51, v213, v51
	v_exp_f32_e32 v196, v52
	v_sub_f32_e32 v52, v73, v231
	v_add_f32_e32 v51, v214, v51
	v_exp_f32_e32 v199, v52
	v_sub_f32_e32 v52, v74, v231
	v_add_f32_e32 v51, v215, v51
	v_exp_f32_e32 v202, v52
	v_sub_f32_e32 v52, v75, v231
	v_add_f32_e32 v51, v216, v51
	v_exp_f32_e32 v205, v52
	v_sub_f32_e32 v52, v76, v231
	v_add_f32_e32 v51, v196, v51
	v_exp_f32_e32 v207, v52
	v_sub_f32_e32 v52, v77, v231
	v_add_f32_e32 v51, v199, v51
	v_exp_f32_e32 v208, v52
	v_sub_f32_e32 v52, v78, v231
	v_add_f32_e32 v51, v202, v51
	v_exp_f32_e32 v209, v52
	v_sub_f32_e32 v52, v79, v231
	v_add_f32_e32 v51, v205, v51
	v_exp_f32_e32 v210, v52
	v_fma_f32 v32, v32, s0, -v231
	v_add_f32_e32 v51, v207, v51
	v_exp_f32_e32 v76, v32
	v_fma_f32 v33, v33, s0, -v231
	v_add_f32_e32 v51, v208, v51
	v_exp_f32_e32 v79, v33
	v_fma_f32 v33, v34, s0, -v231
	v_add_f32_e32 v51, v209, v51
	v_exp_f32_e32 v186, v33
	v_fma_f32 v33, v35, s0, -v231
	v_add_f32_e32 v51, v210, v51
	v_exp_f32_e32 v189, v33
	v_fma_f32 v33, v36, s0, -v231
	v_add_f32_e32 v32, v76, v51
	v_exp_f32_e32 v192, v33
	v_fma_f32 v33, v37, s0, -v231
	v_add_f32_e32 v32, v79, v32
	v_exp_f32_e32 v194, v33
	v_fma_f32 v33, v38, s0, -v231
	v_add_f32_e32 v32, v186, v32
	v_exp_f32_e32 v198, v33
	v_fma_f32 v33, v39, s0, -v231
	v_add_f32_e32 v32, v189, v32
	v_exp_f32_e32 v200, v33
	v_fma_f32 v33, v40, s0, -v231
	v_add_f32_e32 v32, v192, v32
	v_exp_f32_e32 v153, v33
	v_fma_f32 v33, v41, s0, -v231
	v_add_f32_e32 v32, v194, v32
	v_exp_f32_e32 v185, v33
	v_fma_f32 v33, v42, s0, -v231
	v_add_f32_e32 v32, v198, v32
	v_exp_f32_e32 v190, v33
	v_fma_f32 v33, v43, s0, -v231
	v_add_f32_e32 v32, v200, v32
	v_exp_f32_e32 v193, v33
	v_fma_f32 v33, v44, s0, -v231
	v_add_f32_e32 v32, v153, v32
	v_exp_f32_e32 v195, v33
	v_fma_f32 v33, v45, s0, -v231
	v_add_f32_e32 v32, v185, v32
	v_exp_f32_e32 v197, v33
	v_fma_f32 v33, v46, s0, -v231
	v_add_f32_e32 v32, v190, v32
	v_exp_f32_e32 v201, v33
	v_fma_f32 v33, v47, s0, -v231
	v_add_f32_e32 v32, v193, v32
	v_exp_f32_e32 v204, v33
	v_fma_f32 v16, v16, s0, -v231
	v_add_f32_e32 v32, v195, v32
	v_exp_f32_e32 v64, v16
	v_fma_f32 v17, v17, s0, -v231
	v_add_f32_e32 v32, v197, v32
	v_exp_f32_e32 v66, v17
	v_fma_f32 v17, v18, s0, -v231
	v_add_f32_e32 v32, v201, v32
	v_exp_f32_e32 v70, v17
	v_fma_f32 v17, v19, s0, -v231
	v_add_f32_e32 v32, v204, v32
	v_exp_f32_e32 v72, v17
	v_fma_f32 v17, v20, s0, -v231
	v_add_f32_e32 v16, v64, v32
	v_exp_f32_e32 v74, v17
	v_fma_f32 v17, v21, s0, -v231
	v_add_f32_e32 v16, v66, v16
	v_exp_f32_e32 v77, v17
	v_fma_f32 v17, v22, s0, -v231
	v_add_f32_e32 v16, v70, v16
	v_exp_f32_e32 v184, v17
	v_fma_f32 v17, v23, s0, -v231
	v_add_f32_e32 v16, v72, v16
	v_exp_f32_e32 v187, v17
	v_fma_f32 v17, v24, s0, -v231
	v_add_f32_e32 v16, v74, v16
	v_exp_f32_e32 v67, v17
	v_fma_f32 v17, v25, s0, -v231
	v_add_f32_e32 v16, v77, v16
	v_exp_f32_e32 v69, v17
	v_fma_f32 v17, v26, s0, -v231
	v_add_f32_e32 v16, v184, v16
	v_exp_f32_e32 v73, v17
	v_fma_f32 v17, v27, s0, -v231
	v_add_f32_e32 v16, v187, v16
	v_exp_f32_e32 v75, v17
	v_fma_f32 v17, v28, s0, -v231
	v_add_f32_e32 v16, v67, v16
	v_exp_f32_e32 v78, v17
	v_fma_f32 v17, v29, s0, -v231
	v_add_f32_e32 v16, v69, v16
	v_exp_f32_e32 v182, v17
	v_fma_f32 v17, v30, s0, -v231
	v_add_f32_e32 v16, v73, v16
	v_exp_f32_e32 v188, v17
	v_fma_f32 v17, v31, s0, -v231
	v_add_f32_e32 v16, v75, v16
	v_exp_f32_e32 v191, v17
	v_fma_f32 v0, v0, s0, -v231
	v_add_f32_e32 v16, v78, v16
	v_exp_f32_e32 v51, v0
	v_fma_f32 v1, v1, s0, -v231
	v_add_f32_e32 v16, v182, v16
	v_exp_f32_e32 v52, v1
	v_fma_f32 v1, v2, s0, -v231
	v_add_f32_e32 v16, v188, v16
	v_exp_f32_e32 v57, v1
	v_fma_f32 v1, v3, s0, -v231
	v_add_f32_e32 v16, v191, v16
	v_exp_f32_e32 v61, v1
	v_fma_f32 v1, v4, s0, -v231
	v_add_f32_e32 v0, v51, v16
	v_exp_f32_e32 v63, v1
	v_fma_f32 v1, v5, s0, -v231
	v_add_f32_e32 v0, v52, v0
	v_exp_f32_e32 v65, v1
	v_fma_f32 v1, v6, s0, -v231
	v_add_f32_e32 v0, v57, v0
	v_exp_f32_e32 v68, v1
	v_fma_f32 v1, v7, s0, -v231
	v_add_f32_e32 v0, v61, v0
	v_exp_f32_e32 v71, v1
	v_fma_f32 v1, v8, s0, -v231
	v_add_f32_e32 v0, v63, v0
	v_exp_f32_e32 v53, v1
	v_fma_f32 v1, v9, s0, -v231
	v_add_f32_e32 v0, v65, v0
	v_exp_f32_e32 v54, v1
	v_fma_f32 v1, v10, s0, -v231
	v_add_f32_e32 v0, v68, v0
	v_exp_f32_e32 v55, v1
	v_fma_f32 v1, v11, s0, -v231
	v_add_f32_e32 v0, v71, v0
	v_exp_f32_e32 v56, v1
	v_fma_f32 v1, v12, s0, -v231
	v_add_f32_e32 v0, v53, v0
	v_exp_f32_e32 v58, v1
	v_fma_f32 v1, v13, s0, -v231
	v_add_f32_e32 v0, v54, v0
	v_exp_f32_e32 v59, v1
	v_fma_f32 v1, v14, s0, -v231
	v_add_f32_e32 v0, v55, v0
	v_exp_f32_e32 v60, v1
	v_fma_f32 v1, v15, s0, -v231
	v_add_f32_e32 v0, v56, v0
	v_exp_f32_e32 v62, v1
	v_sub_f32_e32 v1, v48, v231
	v_add_f32_e32 v0, v58, v0
	v_exp_f32_e32 v43, v1
	v_sub_f32_e32 v1, v49, v231
	v_add_f32_e32 v0, v59, v0
	v_exp_f32_e32 v44, v1
	v_sub_f32_e32 v1, v50, v231
	v_add_f32_e32 v0, v60, v0
	v_exp_f32_e32 v45, v1
	v_sub_f32_e32 v1, v217, v231
	v_add_f32_e32 v0, v62, v0
	v_exp_f32_e32 v46, v1
	v_sub_f32_e32 v1, v218, v231
	v_add_f32_e32 v0, v43, v0
	v_exp_f32_e32 v47, v1
	v_sub_f32_e32 v1, v219, v231
	v_add_f32_e32 v0, v44, v0
	v_exp_f32_e32 v48, v1
	v_sub_f32_e32 v1, v220, v231
	v_add_f32_e32 v0, v45, v0
	v_exp_f32_e32 v49, v1
	v_sub_f32_e32 v1, v221, v231
	v_add_f32_e32 v0, v46, v0
	v_exp_f32_e32 v50, v1
	v_sub_f32_e32 v1, v222, v231
	v_add_f32_e32 v0, v47, v0
	v_exp_f32_e32 v35, v1
	v_sub_f32_e32 v1, v223, v231
	v_add_f32_e32 v0, v48, v0
	v_exp_f32_e32 v36, v1
	v_sub_f32_e32 v1, v224, v231
	v_add_f32_e32 v0, v49, v0
	v_exp_f32_e32 v37, v1
	v_sub_f32_e32 v1, v225, v231
	v_add_f32_e32 v0, v50, v0
	v_exp_f32_e32 v38, v1
	v_sub_f32_e32 v1, v226, v231
	v_add_f32_e32 v0, v35, v0
	v_exp_f32_e32 v39, v1
	v_sub_f32_e32 v1, v227, v231
	v_add_f32_e32 v0, v36, v0
	v_exp_f32_e32 v40, v1
	v_sub_f32_e32 v1, v228, v231
	v_add_f32_e32 v0, v37, v0
	v_exp_f32_e32 v41, v1
	v_sub_f32_e32 v1, v229, v231
	v_add_f32_e32 v0, v38, v0
	v_exp_f32_e32 v42, v1
	v_add_f32_e32 v0, v39, v0
	v_add_f32_e32 v0, v40, v0
	v_add_f32_e32 v0, v41, v0
	v_add_f32_e32 v32, v42, v0
	v_sub_f32_e32 v0, v179, v231
	v_exp_f32_e32 v34, v0
	v_cvt_pk_bf16_f32 v0, v203, v206
	v_add_u32_e32 v206, v160, v161
	v_add_u32_e32 v203, v160, v162
	ds_read_b64_tr_b16 v[4:5], v206 offset:36864
	ds_read_b64_tr_b16 v[6:7], v206 offset:37888
	ds_read_b64_tr_b16 v[8:9], v203 offset:36864
	ds_read_b64_tr_b16 v[10:11], v203 offset:37888
	v_cvt_pk_bf16_f32 v1, v211, v212
	v_cvt_pk_bf16_f32 v2, v213, v214
	v_cvt_pk_bf16_f32 v3, v215, v216
	v_cvt_pk_bf16_f32 v214, v207, v208
	v_cvt_pk_bf16_f32 v215, v209, v210
	s_waitcnt lgkmcnt(2)
	v_mfma_f32_32x32x16_bf16 v[16:31], v[4:7], v[0:3], 0
	ds_read_b64_tr_b16 v[208:209], v206 offset:38912
	ds_read_b64_tr_b16 v[210:211], v206 offset:39936
	ds_read_b64_tr_b16 v[216:217], v203 offset:38912
	ds_read_b64_tr_b16 v[218:219], v203 offset:39936
	v_cvt_pk_bf16_f32 v212, v196, v199
	v_cvt_pk_bf16_f32 v213, v202, v205
	v_cvt_pk_bf16_f32 v193, v190, v193
	v_cvt_pk_bf16_f32 v73, v73, v75
	v_cvt_pk_bf16_f32 v75, v188, v191
	v_cvt_pk_bf16_f32 v45, v45, v46
	s_waitcnt lgkmcnt(4)
	v_mfma_f32_32x32x16_bf16 v[0:15], v[8:11], v[0:3], 0
	v_cvt_pk_bf16_f32 v46, v47, v48
	v_cvt_pk_bf16_f32 v47, v49, v50
	v_cvt_pk_bf16_f32 v44, v43, v44
	ds_bpermute_b32 v33, v230, v32
	v_cvt_pk_bf16_f32 v37, v37, v38
	v_cvt_pk_bf16_f32 v38, v39, v40
	v_cvt_pk_bf16_f32 v39, v41, v42
	s_waitcnt lgkmcnt(3)
	v_mfma_f32_32x32x16_bf16 v[16:31], v[208:211], v[212:215], v[16:31]
	v_cvt_pk_bf16_f32 v208, v76, v79
	v_cvt_pk_bf16_f32 v209, v186, v189
	v_cvt_pk_bf16_f32 v210, v192, v194
	v_cvt_pk_bf16_f32 v211, v198, v200
	v_cvt_pk_bf16_f32 v194, v195, v197
	v_cvt_pk_bf16_f32 v192, v153, v185
	v_cvt_pk_bf16_f32 v195, v201, v204
	s_waitcnt lgkmcnt(1)
	v_mfma_f32_32x32x16_bf16 v[0:15], v[216:219], v[212:215], v[0:15]
	ds_read_b64_tr_b16 v[212:213], v206 offset:40960
	ds_read_b64_tr_b16 v[214:215], v206 offset:41984
	ds_read_b64_tr_b16 v[216:217], v203 offset:40960
	ds_read_b64_tr_b16 v[218:219], v203 offset:41984
	v_cvt_pk_bf16_f32 v36, v35, v36
	s_waitcnt lgkmcnt(4)
	v_add_f32_e32 v32, v32, v33
	v_add_f32_e32 v32, v34, v32
	s_waitcnt lgkmcnt(2)
	v_mfma_f32_32x32x16_bf16 v[16:31], v[212:215], v[208:211], v[16:31]
	s_waitcnt lgkmcnt(0)
	v_mfma_f32_32x32x16_bf16 v[0:15], v[216:219], v[208:211], v[0:15]
	ds_read_b64_tr_b16 v[196:197], v206 offset:43008
	ds_read_b64_tr_b16 v[198:199], v206 offset:44032
	ds_read_b64_tr_b16 v[208:209], v203 offset:43008
	ds_read_b64_tr_b16 v[210:211], v203 offset:44032
	s_waitcnt lgkmcnt(2)
	v_mfma_f32_32x32x16_bf16 v[16:31], v[196:199], v[192:195], v[16:31]
	s_waitcnt lgkmcnt(0)
	v_mfma_f32_32x32x16_bf16 v[0:15], v[208:211], v[192:195], v[0:15]
	v_cvt_pk_bf16_f32 v195, v184, v187
	ds_read_b64_tr_b16 v[184:185], v206 offset:45056
	ds_read_b64_tr_b16 v[186:187], v206 offset:46080
	ds_read_b64_tr_b16 v[196:197], v203 offset:45056
	ds_read_b64_tr_b16 v[198:199], v203 offset:46080
	v_cvt_pk_bf16_f32 v192, v64, v66
	v_cvt_pk_bf16_f32 v193, v70, v72
	v_cvt_pk_bf16_f32 v194, v74, v77
	v_cvt_pk_bf16_f32 v74, v78, v182
	v_cvt_pk_bf16_f32 v72, v67, v69
	s_waitcnt lgkmcnt(2)
	v_mfma_f32_32x32x16_bf16 v[16:31], v[184:187], v[192:195], v[16:31]
	ds_read_b64_tr_b16 v[76:77], v206 offset:47104
	ds_read_b64_tr_b16 v[78:79], v206 offset:48128
	ds_read_b64_tr_b16 v[184:185], v203 offset:47104
	ds_read_b64_tr_b16 v[186:187], v203 offset:48128
	s_waitcnt lgkmcnt(4)
	v_mfma_f32_32x32x16_bf16 v[0:15], v[196:199], v[192:195], v[0:15]
	s_waitcnt lgkmcnt(2)
	v_mfma_f32_32x32x16_bf16 v[16:31], v[76:79], v[72:75], v[16:31]
	s_waitcnt lgkmcnt(0)
	v_mfma_f32_32x32x16_bf16 v[0:15], v[184:187], v[72:75], v[0:15]
	v_cvt_pk_bf16_f32 v74, v63, v65
	v_cvt_pk_bf16_f32 v75, v68, v71
	ds_read_b64_tr_b16 v[64:65], v206 offset:49152
	ds_read_b64_tr_b16 v[66:67], v206 offset:50176
	ds_read_b64_tr_b16 v[68:69], v203 offset:49152
	ds_read_b64_tr_b16 v[70:71], v203 offset:50176
	v_cvt_pk_bf16_f32 v72, v51, v52
	v_cvt_pk_bf16_f32 v73, v57, v61
	v_cvt_pk_bf16_f32 v52, v53, v54
	v_cvt_pk_bf16_f32 v53, v55, v56
	s_waitcnt lgkmcnt(2)
	v_mfma_f32_32x32x16_bf16 v[16:31], v[64:67], v[72:75], v[16:31]
	v_cvt_pk_bf16_f32 v54, v58, v59
	v_cvt_pk_bf16_f32 v55, v60, v62
	ds_read_b64_tr_b16 v[56:57], v206 offset:51200
	ds_read_b64_tr_b16 v[58:59], v206 offset:52224
	ds_read_b64_tr_b16 v[60:61], v203 offset:51200
	ds_read_b64_tr_b16 v[62:63], v203 offset:52224
	s_waitcnt lgkmcnt(4)
	v_mfma_f32_32x32x16_bf16 v[0:15], v[68:71], v[72:75], v[0:15]
	s_waitcnt lgkmcnt(2)
	v_mfma_f32_32x32x16_bf16 v[16:31], v[56:59], v[52:55], v[16:31]
	s_waitcnt lgkmcnt(0)
	v_mfma_f32_32x32x16_bf16 v[0:15], v[60:63], v[52:55], v[0:15]
	ds_read_b64_tr_b16 v[48:49], v206 offset:53248
	ds_read_b64_tr_b16 v[50:51], v206 offset:54272
	ds_read_b64_tr_b16 v[52:53], v203 offset:53248
	ds_read_b64_tr_b16 v[54:55], v203 offset:54272
	s_waitcnt lgkmcnt(2)
	v_mfma_f32_32x32x16_bf16 v[16:31], v[48:51], v[44:47], v[16:31]
	s_waitcnt lgkmcnt(0)
	v_mfma_f32_32x32x16_bf16 v[0:15], v[52:55], v[44:47], v[0:15]
	ds_read_b64_tr_b16 v[40:41], v206 offset:55296
	ds_read_b64_tr_b16 v[42:43], v206 offset:56320
	ds_read_b64_tr_b16 v[44:45], v203 offset:55296
	ds_read_b64_tr_b16 v[46:47], v203 offset:56320
	s_waitcnt lgkmcnt(2)
	v_mfma_f32_32x32x16_bf16 v[16:31], v[40:43], v[36:39], v[16:31]
	s_waitcnt lgkmcnt(0)
	v_mfma_f32_32x32x16_bf16 v[0:15], v[44:47], v[36:39], v[0:15]
	s_cbranch_execnz .LBB0_485

.LBB0_485:
	s_lshl_b64 s[18:19], s[80:81], 11
	v_div_scale_f32 v33, s[80:81], v32, v32, 1.0
	v_rcp_f32_e32 v34, v33
	s_add_u32 s18, s48, s18
	s_addc_u32 s19, s49, s19
	s_add_u32 s18, s18, s82
	v_fma_f32 v35, -v33, v34, 1.0
	v_fmac_f32_e32 v34, v35, v34
	v_div_scale_f32 v35, vcc, 1.0, v32, 1.0
	v_mul_f32_e32 v36, v35, v34
	v_fma_f32 v37, -v33, v36, v35
	v_fmac_f32_e32 v36, v37, v34
	v_fma_f32 v33, -v33, v36, v35
	v_div_fmas_f32 v33, v33, v34, v36
	s_addc_u32 s19, s19, s83
	v_div_fixup_f32 v32, v33, v32, 1.0
	v_lshl_add_u64 v[34:35], s[18:19], 0, v[144:145]
	v_mov_b32_e32 v153, v145
	v_pk_mul_f32 v[16:17], v[32:33], v[16:17] op_sel_hi:[0,1]
	v_pk_mul_f32 v[18:19], v[32:33], v[18:19] op_sel_hi:[0,1]
	v_pk_mul_f32 v[20:21], v[32:33], v[20:21] op_sel_hi:[0,1]
	v_pk_mul_f32 v[22:23], v[32:33], v[22:23] op_sel_hi:[0,1]
	v_pk_mul_f32 v[24:25], v[32:33], v[24:25] op_sel_hi:[0,1]
	v_pk_mul_f32 v[26:27], v[32:33], v[26:27] op_sel_hi:[0,1]
	v_pk_mul_f32 v[28:29], v[32:33], v[28:29] op_sel_hi:[0,1]
	v_pk_mul_f32 v[30:31], v[32:33], v[30:31] op_sel_hi:[0,1]
	v_pk_mul_f32 v[0:1], v[32:33], v[0:1] op_sel_hi:[0,1]
	v_pk_mul_f32 v[2:3], v[32:33], v[2:3] op_sel_hi:[0,1]
	v_pk_mul_f32 v[4:5], v[32:33], v[4:5] op_sel_hi:[0,1]
	v_pk_mul_f32 v[6:7], v[32:33], v[6:7] op_sel_hi:[0,1]
	v_pk_mul_f32 v[8:9], v[32:33], v[8:9] op_sel_hi:[0,1]
	v_pk_mul_f32 v[10:11], v[32:33], v[10:11] op_sel_hi:[0,1]
	v_pk_mul_f32 v[12:13], v[32:33], v[12:13] op_sel_hi:[0,1]
	v_pk_mul_f32 v[14:15], v[32:33], v[14:15] op_sel_hi:[0,1]
	v_lshl_add_u64 v[34:35], v[34:35], 0, v[152:153]
	v_lshl_add_u64 v[34:35], v[34:35], 0, v[152:153]
	v_cvt_pk_bf16_f32 v16, v16, v17
	v_cvt_pk_bf16_f32 v17, v18, v19
	v_cvt_pk_bf16_f32 v18, v20, v21
	v_cvt_pk_bf16_f32 v19, v22, v23
	v_cvt_pk_bf16_f32 v20, v24, v25
	v_cvt_pk_bf16_f32 v21, v26, v27
	v_cvt_pk_bf16_f32 v22, v28, v29
	v_cvt_pk_bf16_f32 v23, v30, v31
	v_cvt_pk_bf16_f32 v0, v0, v1
	v_cvt_pk_bf16_f32 v1, v2, v3
	v_cvt_pk_bf16_f32 v2, v4, v5
	v_cvt_pk_bf16_f32 v3, v6, v7
	v_cvt_pk_bf16_f32 v4, v8, v9
	v_cvt_pk_bf16_f32 v5, v10, v11
	v_cvt_pk_bf16_f32 v6, v12, v13
	v_cvt_pk_bf16_f32 v7, v14, v15
	s_or_b32 s46, s17, s94
	s_and_b64 vcc, exec, s[86:87]
	s_nop 1
	v_permlane32_swap_b32 v16, v18
	v_permlane32_swap_b32 v17, v19
	v_permlane32_swap_b32 v20, v22
	v_permlane32_swap_b32 v21, v23
	v_permlane32_swap_b32 v0, v2
	v_permlane32_swap_b32 v1, v3
	v_permlane32_swap_b32 v4, v6
	v_permlane32_swap_b32 v5, v7
	global_store_dwordx4 v[34:35], v[16:19], off
	global_store_dwordx4 v[34:35], v[20:23], off offset:32
	global_store_dwordx4 v[34:35], v[0:3], off offset:64
	global_store_dwordx4 v[34:35], v[4:7], off offset:96
	s_nop 1
	s_cbranch_vccz .LBB0_488
	ds_read_b128 v[0:3], v178
	ds_read_b128 v[4:7], v178 offset:32
	s_waitcnt lgkmcnt(1)
	v_mfma_f32_32x32x16_bf16 v[64:79], v[0:3], v[124:127], 0
	ds_read_b128 v[0:3], v178 offset:64
	ds_read_b128 v[48:51], v178 offset:13856
	ds_read_b128 v[128:131], v178 offset:18464
	s_waitcnt lgkmcnt(3)
	v_mfma_f32_32x32x16_bf16 v[64:79], v[4:7], v[120:123], v[64:79]
	s_waitcnt lgkmcnt(2)
	v_mfma_f32_32x32x16_bf16 v[64:79], v[0:3], v[112:115], v[64:79]
	ds_read_b128 v[0:3], v178 offset:96
	s_waitcnt lgkmcnt(0)
	v_mfma_f32_32x32x16_bf16 v[64:79], v[0:3], v[116:119], v[64:79]
	ds_read_b128 v[0:3], v178 offset:4608
	s_waitcnt lgkmcnt(0)
	v_mfma_f32_32x32x16_bf16 v[32:47], v[0:3], v[124:127], 0
	ds_read_b128 v[0:3], v178 offset:4640
	s_nop 7
	v_mul_f32_e32 v64, 0x3e38aa3b, v64
	v_mul_f32_e32 v65, 0x3e38aa3b, v65
	v_mul_f32_e32 v66, 0x3e38aa3b, v66
	v_mul_f32_e32 v67, 0x3e38aa3b, v67
	v_mul_f32_e32 v68, 0x3e38aa3b, v68
	v_mul_f32_e32 v69, 0x3e38aa3b, v69
	s_waitcnt lgkmcnt(0)
	v_mfma_f32_32x32x16_bf16 v[32:47], v[0:3], v[120:123], v[32:47]
	ds_read_b128 v[0:3], v178 offset:4672
	v_mul_f32_e32 v70, 0x3e38aa3b, v70
	v_mul_f32_e32 v71, 0x3e38aa3b, v71
	v_mul_f32_e32 v72, 0x3e38aa3b, v72
	v_mul_f32_e32 v73, 0x3e38aa3b, v73
	v_mul_f32_e32 v74, 0x3e38aa3b, v74
	v_mul_f32_e32 v75, 0x3e38aa3b, v75
	s_waitcnt lgkmcnt(0)
	v_mfma_f32_32x32x16_bf16 v[32:47], v[0:3], v[112:115], v[32:47]
	ds_read_b128 v[0:3], v178 offset:4704
	v_mul_f32_e32 v76, 0x3e38aa3b, v76
	v_mul_f32_e32 v77, 0x3e38aa3b, v77
	v_mul_f32_e32 v78, 0x3e38aa3b, v78
	v_mul_f32_e32 v79, 0x3e38aa3b, v79
	s_waitcnt lgkmcnt(0)
	v_mfma_f32_32x32x16_bf16 v[32:47], v[0:3], v[116:119], v[32:47]
	ds_read_b128 v[0:3], v178 offset:9216
	s_waitcnt lgkmcnt(0)
	v_mfma_f32_32x32x16_bf16 v[16:31], v[0:3], v[124:127], 0
	ds_read_b128 v[0:3], v178 offset:9248
	s_nop 7
	v_mul_f32_e32 v133, 0x3e38aa3b, v33
	s_waitcnt lgkmcnt(0)
	v_mfma_f32_32x32x16_bf16 v[16:31], v[0:3], v[120:123], v[16:31]
	ds_read_b128 v[0:3], v178 offset:9280
	s_waitcnt lgkmcnt(0)
	v_mfma_f32_32x32x16_bf16 v[16:31], v[0:3], v[112:115], v[16:31]
	ds_read_b128 v[0:3], v178 offset:9312
	s_waitcnt lgkmcnt(0)
	v_mfma_f32_32x32x16_bf16 v[16:31], v[0:3], v[116:119], v[16:31]
	ds_read_b128 v[0:3], v178 offset:13824
	s_waitcnt lgkmcnt(0)
	v_mfma_f32_32x32x16_bf16 v[0:15], v[0:3], v[124:127], 0
	v_mfma_f32_32x32x16_bf16 v[0:15], v[48:51], v[120:123], v[0:15]
	ds_read_b128 v[48:51], v178 offset:13888
	s_waitcnt lgkmcnt(0)
	v_mfma_f32_32x32x16_bf16 v[0:15], v[48:51], v[112:115], v[0:15]
	ds_read_b128 v[48:51], v178 offset:13920
	s_waitcnt lgkmcnt(0)
	v_mfma_f32_32x32x16_bf16 v[0:15], v[48:51], v[116:119], v[0:15]
	ds_read_b128 v[48:51], v178 offset:18432
	s_waitcnt lgkmcnt(0)
	v_mfma_f32_32x32x16_bf16 v[48:63], v[48:51], v[124:127], 0
	v_mfma_f32_32x32x16_bf16 v[48:63], v[128:131], v[120:123], v[48:63]
	ds_read_b128 v[128:131], v178 offset:18496
	s_waitcnt lgkmcnt(0)
	v_mfma_f32_32x32x16_bf16 v[48:63], v[128:131], v[112:115], v[48:63]
	ds_read_b128 v[128:131], v178 offset:18528
	s_waitcnt lgkmcnt(0)
	v_mfma_f32_32x32x16_bf16 v[48:63], v[128:131], v[116:119], v[48:63]
	v_add_u32_e32 v128, s17, v164
	v_or_b32_e32 v130, s46, v158
	v_sub_u32_e32 v131, v130, v128
	v_cmp_gt_i32_e32 vcc, s92, v131
	v_sub_u32_e32 v132, v128, v130
	v_add_u32_e32 v129, 0x9b, v128
	v_cndmask_b32_e32 v64, v177, v64, vcc
	v_cmp_lt_i32_e32 vcc, s93, v132
	s_nop 3
	v_mul_f32_e32 v48, 0x3e38aa3b, v48
	v_mul_f32_e32 v49, 0x3e38aa3b, v49
	v_cndmask_b32_e32 v65, v177, v65, vcc
	v_cmp_gt_i32_e32 vcc, s4, v131
	v_max3_f32 v132, v64, s1, v65
	v_mul_f32_e32 v50, 0x3e38aa3b, v50
	v_cndmask_b32_e32 v66, v177, v66, vcc
	v_cmp_gt_i32_e32 vcc, s5, v131
	v_mul_f32_e32 v51, 0x3e38aa3b, v51
	v_mul_f32_e32 v52, 0x3e38aa3b, v52
	v_cndmask_b32_e32 v67, v177, v67, vcc
	v_cmp_gt_i32_e32 vcc, s6, v131
	v_max3_f32 v132, v132, v66, v67
	v_mul_f32_e32 v53, 0x3e38aa3b, v53
	v_cndmask_b32_e32 v68, v177, v68, vcc
	v_cmp_gt_i32_e32 vcc, s7, v131
	s_nop 1
	v_cndmask_b32_e32 v69, v177, v69, vcc
	v_cmp_gt_i32_e32 vcc, s8, v131
	v_max3_f32 v132, v132, v68, v69
	s_nop 0
	v_cndmask_b32_e32 v70, v177, v70, vcc
	v_cmp_gt_i32_e32 vcc, s9, v131
	s_nop 1
	v_cndmask_b32_e32 v71, v177, v71, vcc
	v_cmp_gt_i32_e32 vcc, s33, v131
	v_max3_f32 v132, v132, v70, v71
	s_nop 0
	v_cndmask_b32_e32 v72, v177, v72, vcc
	v_cmp_gt_i32_e32 vcc, s10, v131
	s_nop 1
	v_cndmask_b32_e32 v73, v177, v73, vcc
	v_cmp_gt_i32_e32 vcc, s11, v131
	v_max3_f32 v132, v132, v72, v73
	s_nop 0
	v_cndmask_b32_e32 v74, v177, v74, vcc
	v_cmp_gt_i32_e32 vcc, s12, v131
	s_nop 1
	v_cndmask_b32_e32 v75, v177, v75, vcc
	v_cmp_gt_i32_e32 vcc, s13, v131
	v_max3_f32 v132, v132, v74, v75
	s_nop 0
	v_cndmask_b32_e32 v76, v177, v76, vcc
	v_cmp_gt_i32_e32 vcc, s14, v131
	s_nop 1
	v_cndmask_b32_e32 v77, v177, v77, vcc
	v_cmp_gt_i32_e32 vcc, s15, v131
	v_max3_f32 v132, v132, v76, v77
	s_nop 0
	v_cndmask_b32_e32 v78, v177, v78, vcc
	v_cmp_gt_i32_e32 vcc, s97, v131
	s_nop 1
	v_cndmask_b32_e32 v79, v177, v79, vcc
	v_max3_f32 v131, v132, v78, v79
	v_mul_f32_e32 v132, 0x3e38aa3b, v32
	v_max3_f32 v131, v131, v132, v133
	v_max_f32_e32 v132, v34, v35
	v_max3_f32 v132, v132, v36, v37
	v_max3_f32 v132, v132, v38, v39
	v_max3_f32 v132, v132, v40, v41
	v_max3_f32 v132, v132, v42, v43
	v_max3_f32 v132, v132, v44, v45
	v_max3_f32 v132, v132, v46, v47
	v_max3_f32 v132, v132, v16, v17
	v_max3_f32 v132, v132, v18, v19
	v_max3_f32 v132, v132, v20, v21
	v_max3_f32 v132, v132, v22, v23
	v_max3_f32 v132, v132, v24, v25
	v_max3_f32 v132, v132, v26, v27
	v_max3_f32 v132, v132, v28, v29
	v_max3_f32 v132, v132, v30, v31
	v_max3_f32 v132, v132, v0, v1
	v_max3_f32 v132, v132, v2, v3
	v_max3_f32 v132, v132, v4, v5
	v_max3_f32 v132, v132, v6, v7
	v_max3_f32 v132, v132, v8, v9
	v_max3_f32 v132, v132, v10, v11
	v_max3_f32 v132, v132, v12, v13
	v_max3_f32 v132, v132, v14, v15
	v_mul_f32_e32 v132, 0x3e38aa3b, v132
	v_max_f32_e32 v131, v131, v132
	v_add_u32_e32 v132, 0x80, v128
	v_cmp_ge_u32_e32 vcc, v130, v132
	v_add_u32_e32 v132, 0x81, v128
	s_nop 0
	v_cndmask_b32_e32 v48, v177, v48, vcc
	v_cmp_ge_u32_e32 vcc, v130, v132
	v_add_u32_e32 v132, 0x82, v128
	s_nop 0
	v_cndmask_b32_e32 v49, v177, v49, vcc
	v_cmp_ge_u32_e32 vcc, v130, v132
	v_add_u32_e32 v132, 0x83, v128
	v_max3_f32 v131, v131, v48, v49
	v_cndmask_b32_e32 v50, v177, v50, vcc
	v_cmp_ge_u32_e32 vcc, v130, v132
	s_nop 1
	v_cndmask_b32_e32 v201, v177, v51, vcc
	v_max3_f32 v51, v131, v50, v201
	v_add_u32_e32 v131, 0x88, v128
	v_cmp_ge_u32_e32 vcc, v130, v131
	s_nop 1
	v_cndmask_b32_e32 v202, v177, v52, vcc
	v_add_u32_e32 v52, 0x89, v128
	v_cmp_ge_u32_e32 vcc, v130, v52
	v_add_u32_e32 v52, 0x8a, v128
	s_nop 0
	v_cndmask_b32_e32 v203, v177, v53, vcc
	v_mul_f32_e32 v53, 0x3e38aa3b, v54
	v_cmp_ge_u32_e32 vcc, v130, v52
	v_add_u32_e32 v52, 0x8b, v128
	v_max3_f32 v51, v51, v202, v203
	v_cndmask_b32_e32 v204, v177, v53, vcc
	v_mul_f32_e32 v53, 0x3e38aa3b, v55
	v_cmp_ge_u32_e32 vcc, v130, v52
	v_add_u32_e32 v52, 0x90, v128
	s_nop 0
	v_cndmask_b32_e32 v205, v177, v53, vcc
	v_mul_f32_e32 v53, 0x3e38aa3b, v56
	v_cmp_ge_u32_e32 vcc, v130, v52
	v_add_u32_e32 v52, 0x91, v128
	v_max3_f32 v51, v51, v204, v205
	v_cndmask_b32_e32 v206, v177, v53, vcc
	v_mul_f32_e32 v53, 0x3e38aa3b, v57
	v_cmp_ge_u32_e32 vcc, v130, v52
	v_add_u32_e32 v52, 0x92, v128
	s_nop 0
	v_cndmask_b32_e32 v207, v177, v53, vcc
	v_mul_f32_e32 v53, 0x3e38aa3b, v58
	v_cmp_ge_u32_e32 vcc, v130, v52
	v_add_u32_e32 v52, 0x93, v128
	v_max3_f32 v51, v51, v206, v207
	v_cndmask_b32_e32 v208, v177, v53, vcc
	v_mul_f32_e32 v53, 0x3e38aa3b, v59
	v_cmp_ge_u32_e32 vcc, v130, v52
	v_add_u32_e32 v52, 0x98, v128
	s_nop 0
	v_cndmask_b32_e32 v209, v177, v53, vcc
	v_mul_f32_e32 v53, 0x3e38aa3b, v60
	v_cmp_ge_u32_e32 vcc, v130, v52
	v_add_u32_e32 v52, 0x99, v128
	v_max3_f32 v51, v51, v208, v209
	v_cndmask_b32_e32 v210, v177, v53, vcc
	v_mul_f32_e32 v53, 0x3e38aa3b, v61
	v_cmp_ge_u32_e32 vcc, v130, v52
	v_add_u32_e32 v52, 0x9a, v128
	s_nop 0
	v_cndmask_b32_e32 v211, v177, v53, vcc
	v_mul_f32_e32 v53, 0x3e38aa3b, v62
	v_cmp_ge_u32_e32 vcc, v130, v52
	v_mul_f32_e32 v52, 0x3e38aa3b, v63
	v_max3_f32 v51, v51, v210, v211
	v_cndmask_b32_e32 v212, v177, v53, vcc
	v_cmp_ge_u32_e32 vcc, v130, v129
	v_and_b32_e32 v53, 64, v180
	v_add_u32_e32 v53, 64, v53
	v_cndmask_b32_e32 v213, v177, v52, vcc
	v_xor_b32_e32 v52, 32, v180
	v_cmp_lt_i32_e32 vcc, v52, v53
	v_max3_f32 v51, v51, v212, v213
	s_nop 0
	v_cndmask_b32_e32 v52, v180, v52, vcc
	v_lshlrev_b32_e32 v214, 2, v52
	ds_bpermute_b32 v52, v214, v51
	s_waitcnt lgkmcnt(0)
	v_max3_f32 v215, v51, v52, v179
	v_sub_f32_e32 v51, v64, v215
	v_exp_f32_e32 v187, v51
	v_sub_f32_e32 v52, v65, v215
	v_exp_f32_e32 v190, v52
	v_sub_f32_e32 v52, v66, v215
	v_exp_f32_e32 v195, v52
	v_sub_f32_e32 v52, v67, v215
	v_exp_f32_e32 v196, v52
	v_sub_f32_e32 v52, v68, v215
	v_add_f32_e32 v51, 0, v187
	v_exp_f32_e32 v197, v52
	v_sub_f32_e32 v52, v69, v215
	v_add_f32_e32 v51, v190, v51
	v_exp_f32_e32 v198, v52
	v_sub_f32_e32 v52, v70, v215
	v_add_f32_e32 v51, v195, v51
	v_exp_f32_e32 v199, v52
	v_sub_f32_e32 v52, v71, v215
	v_add_f32_e32 v51, v196, v51
	v_exp_f32_e32 v200, v52
	v_sub_f32_e32 v52, v72, v215
	v_add_f32_e32 v51, v197, v51
	v_exp_f32_e32 v142, v52
	v_sub_f32_e32 v52, v73, v215
	v_add_f32_e32 v51, v198, v51
	v_exp_f32_e32 v182, v52
	v_sub_f32_e32 v52, v74, v215
	v_add_f32_e32 v51, v199, v51
	v_exp_f32_e32 v186, v52
	v_sub_f32_e32 v52, v75, v215
	v_add_f32_e32 v51, v200, v51
	v_exp_f32_e32 v189, v52
	v_sub_f32_e32 v52, v76, v215
	v_add_f32_e32 v51, v142, v51
	v_exp_f32_e32 v191, v52
	v_sub_f32_e32 v52, v77, v215
	v_add_f32_e32 v51, v182, v51
	v_exp_f32_e32 v192, v52
	v_sub_f32_e32 v52, v78, v215
	v_add_f32_e32 v51, v186, v51
	v_exp_f32_e32 v193, v52
	v_sub_f32_e32 v52, v79, v215
	v_add_f32_e32 v51, v189, v51
	v_exp_f32_e32 v194, v52
	v_fma_f32 v32, v32, s0, -v215
	v_add_f32_e32 v51, v191, v51
	v_exp_f32_e32 v76, v32
	v_fma_f32 v33, v33, s0, -v215
	v_add_f32_e32 v51, v192, v51
	v_exp_f32_e32 v79, v33
	v_fma_f32 v33, v34, s0, -v215
	v_add_f32_e32 v51, v193, v51
	v_exp_f32_e32 v132, v33
	v_fma_f32 v33, v35, s0, -v215
	v_add_f32_e32 v51, v194, v51
	v_exp_f32_e32 v135, v33
	v_fma_f32 v33, v36, s0, -v215
	v_add_f32_e32 v32, v76, v51
	v_exp_f32_e32 v138, v33
	v_fma_f32 v33, v37, s0, -v215
	v_add_f32_e32 v32, v79, v32
	v_exp_f32_e32 v140, v33
	v_fma_f32 v33, v38, s0, -v215
	v_add_f32_e32 v32, v132, v32
	v_exp_f32_e32 v153, v33
	v_fma_f32 v33, v39, s0, -v215
	v_add_f32_e32 v32, v135, v32
	v_exp_f32_e32 v184, v33
	v_fma_f32 v33, v40, s0, -v215
	v_add_f32_e32 v32, v138, v32
	v_exp_f32_e32 v128, v33
	v_fma_f32 v33, v41, s0, -v215
	v_add_f32_e32 v32, v140, v32
	v_exp_f32_e32 v131, v33
	v_fma_f32 v33, v42, s0, -v215
	v_add_f32_e32 v32, v153, v32
	v_exp_f32_e32 v136, v33
	v_fma_f32 v33, v43, s0, -v215
	v_add_f32_e32 v32, v184, v32
	v_exp_f32_e32 v139, v33
	v_fma_f32 v33, v44, s0, -v215
	v_add_f32_e32 v32, v128, v32
	v_exp_f32_e32 v141, v33
	v_fma_f32 v33, v45, s0, -v215
	v_add_f32_e32 v32, v131, v32
	v_exp_f32_e32 v143, v33
	v_fma_f32 v33, v46, s0, -v215
	v_add_f32_e32 v32, v136, v32
	v_exp_f32_e32 v185, v33
	v_fma_f32 v33, v47, s0, -v215
	v_add_f32_e32 v32, v139, v32
	v_exp_f32_e32 v188, v33
	v_fma_f32 v16, v16, s0, -v215
	v_add_f32_e32 v32, v141, v32
	v_exp_f32_e32 v64, v16
	v_fma_f32 v17, v17, s0, -v215
	v_add_f32_e32 v32, v143, v32
	v_exp_f32_e32 v66, v17
	v_fma_f32 v17, v18, s0, -v215
	v_add_f32_e32 v32, v185, v32
	v_exp_f32_e32 v70, v17
	v_fma_f32 v17, v19, s0, -v215
	v_add_f32_e32 v32, v188, v32
	v_exp_f32_e32 v72, v17
	v_fma_f32 v17, v20, s0, -v215
	v_add_f32_e32 v16, v64, v32
	v_exp_f32_e32 v74, v17
	v_fma_f32 v17, v21, s0, -v215
	v_add_f32_e32 v16, v66, v16
	v_exp_f32_e32 v77, v17
	v_fma_f32 v17, v22, s0, -v215
	v_add_f32_e32 v16, v70, v16
	v_exp_f32_e32 v130, v17
	v_fma_f32 v17, v23, s0, -v215
	v_add_f32_e32 v16, v72, v16
	v_exp_f32_e32 v133, v17
	v_fma_f32 v17, v24, s0, -v215
	v_add_f32_e32 v16, v74, v16
	v_exp_f32_e32 v67, v17
	v_fma_f32 v17, v25, s0, -v215
	v_add_f32_e32 v16, v77, v16
	v_exp_f32_e32 v69, v17
	v_fma_f32 v17, v26, s0, -v215
	v_add_f32_e32 v16, v130, v16
	v_exp_f32_e32 v73, v17
	v_fma_f32 v17, v27, s0, -v215
	v_add_f32_e32 v16, v133, v16
	v_exp_f32_e32 v75, v17
	v_fma_f32 v17, v28, s0, -v215
	v_add_f32_e32 v16, v67, v16
	v_exp_f32_e32 v78, v17
	v_fma_f32 v17, v29, s0, -v215
	v_add_f32_e32 v16, v69, v16
	v_exp_f32_e32 v129, v17
	v_fma_f32 v17, v30, s0, -v215
	v_add_f32_e32 v16, v73, v16
	v_exp_f32_e32 v134, v17
	v_fma_f32 v17, v31, s0, -v215
	v_add_f32_e32 v16, v75, v16
	v_exp_f32_e32 v137, v17
	v_fma_f32 v0, v0, s0, -v215
	v_add_f32_e32 v16, v78, v16
	v_exp_f32_e32 v51, v0
	v_fma_f32 v1, v1, s0, -v215
	v_add_f32_e32 v16, v129, v16
	v_exp_f32_e32 v52, v1
	v_fma_f32 v1, v2, s0, -v215
	v_add_f32_e32 v16, v134, v16
	v_exp_f32_e32 v57, v1
	v_fma_f32 v1, v3, s0, -v215
	v_add_f32_e32 v16, v137, v16
	v_exp_f32_e32 v61, v1
	v_fma_f32 v1, v4, s0, -v215
	v_add_f32_e32 v0, v51, v16
	v_exp_f32_e32 v63, v1
	v_fma_f32 v1, v5, s0, -v215
	v_add_f32_e32 v0, v52, v0
	v_exp_f32_e32 v65, v1
	v_fma_f32 v1, v6, s0, -v215
	v_add_f32_e32 v0, v57, v0
	v_exp_f32_e32 v68, v1
	v_fma_f32 v1, v7, s0, -v215
	v_add_f32_e32 v0, v61, v0
	v_exp_f32_e32 v71, v1
	v_fma_f32 v1, v8, s0, -v215
	v_add_f32_e32 v0, v63, v0
	v_exp_f32_e32 v53, v1
	v_fma_f32 v1, v9, s0, -v215
	v_add_f32_e32 v0, v65, v0
	v_exp_f32_e32 v54, v1
	v_fma_f32 v1, v10, s0, -v215
	v_add_f32_e32 v0, v68, v0
	v_exp_f32_e32 v55, v1
	v_fma_f32 v1, v11, s0, -v215
	v_add_f32_e32 v0, v71, v0
	v_exp_f32_e32 v56, v1
	v_fma_f32 v1, v12, s0, -v215
	v_add_f32_e32 v0, v53, v0
	v_exp_f32_e32 v58, v1
	v_fma_f32 v1, v13, s0, -v215
	v_add_f32_e32 v0, v54, v0
	v_exp_f32_e32 v59, v1
	v_fma_f32 v1, v14, s0, -v215
	v_add_f32_e32 v0, v55, v0
	v_exp_f32_e32 v60, v1
	v_fma_f32 v1, v15, s0, -v215
	v_add_f32_e32 v0, v56, v0
	v_exp_f32_e32 v62, v1
	v_sub_f32_e32 v1, v48, v215
	v_add_f32_e32 v0, v58, v0
	v_exp_f32_e32 v43, v1
	v_sub_f32_e32 v1, v49, v215
	v_add_f32_e32 v0, v59, v0
	v_exp_f32_e32 v44, v1
	v_sub_f32_e32 v1, v50, v215
	v_add_f32_e32 v0, v60, v0
	v_exp_f32_e32 v45, v1
	v_sub_f32_e32 v1, v201, v215
	v_add_f32_e32 v0, v62, v0
	v_exp_f32_e32 v46, v1
	v_sub_f32_e32 v1, v202, v215
	v_add_f32_e32 v0, v43, v0
	v_exp_f32_e32 v47, v1
	v_sub_f32_e32 v1, v203, v215
	v_add_f32_e32 v0, v44, v0
	v_exp_f32_e32 v48, v1
	v_sub_f32_e32 v1, v204, v215
	v_add_f32_e32 v0, v45, v0
	v_exp_f32_e32 v49, v1
	v_sub_f32_e32 v1, v205, v215
	v_add_f32_e32 v0, v46, v0
	v_exp_f32_e32 v50, v1
	v_sub_f32_e32 v1, v206, v215
	v_add_f32_e32 v0, v47, v0
	v_exp_f32_e32 v35, v1
	v_sub_f32_e32 v1, v207, v215
	v_add_f32_e32 v0, v48, v0
	v_exp_f32_e32 v36, v1
	v_sub_f32_e32 v1, v208, v215
	v_add_f32_e32 v0, v49, v0
	v_exp_f32_e32 v37, v1
	v_sub_f32_e32 v1, v209, v215
	v_add_f32_e32 v0, v50, v0
	v_exp_f32_e32 v38, v1
	v_sub_f32_e32 v1, v210, v215
	v_add_f32_e32 v0, v35, v0
	v_exp_f32_e32 v39, v1
	v_sub_f32_e32 v1, v211, v215
	v_add_f32_e32 v0, v36, v0
	v_exp_f32_e32 v40, v1
	v_sub_f32_e32 v1, v212, v215
	v_add_f32_e32 v0, v37, v0
	v_exp_f32_e32 v41, v1
	v_sub_f32_e32 v1, v213, v215
	v_add_f32_e32 v0, v38, v0
	v_exp_f32_e32 v42, v1
	v_add_f32_e32 v0, v39, v0
	v_add_f32_e32 v0, v40, v0
	v_add_f32_e32 v0, v41, v0
	v_add_f32_e32 v32, v42, v0
	v_sub_f32_e32 v0, v179, v215
	v_exp_f32_e32 v34, v0
	v_cvt_pk_bf16_f32 v0, v187, v190
	v_add_u32_e32 v190, v165, v161
	v_add_u32_e32 v187, v165, v162
	ds_read_b64_tr_b16 v[4:5], v190 offset:36864
	ds_read_b64_tr_b16 v[6:7], v190 offset:37888
	ds_read_b64_tr_b16 v[8:9], v187 offset:36864
	ds_read_b64_tr_b16 v[10:11], v187 offset:37888
	v_cvt_pk_bf16_f32 v1, v195, v196
	v_cvt_pk_bf16_f32 v2, v197, v198
	v_cvt_pk_bf16_f32 v3, v199, v200
	v_cvt_pk_bf16_f32 v198, v191, v192
	v_cvt_pk_bf16_f32 v199, v193, v194
	s_waitcnt lgkmcnt(2)
	v_mfma_f32_32x32x16_bf16 v[16:31], v[4:7], v[0:3], 0
	ds_read_b64_tr_b16 v[192:193], v190 offset:38912
	ds_read_b64_tr_b16 v[194:195], v190 offset:39936
	ds_read_b64_tr_b16 v[200:201], v187 offset:38912
	ds_read_b64_tr_b16 v[202:203], v187 offset:39936
	v_cvt_pk_bf16_f32 v196, v142, v182
	v_cvt_pk_bf16_f32 v197, v186, v189
	v_cvt_pk_bf16_f32 v139, v136, v139
	v_cvt_pk_bf16_f32 v73, v73, v75
	v_cvt_pk_bf16_f32 v75, v134, v137
	v_cvt_pk_bf16_f32 v45, v45, v46
	s_waitcnt lgkmcnt(4)
	v_mfma_f32_32x32x16_bf16 v[0:15], v[8:11], v[0:3], 0
	v_cvt_pk_bf16_f32 v46, v47, v48
	v_cvt_pk_bf16_f32 v47, v49, v50
	v_cvt_pk_bf16_f32 v44, v43, v44
	ds_bpermute_b32 v33, v214, v32
	v_cvt_pk_bf16_f32 v37, v37, v38
	v_cvt_pk_bf16_f32 v38, v39, v40
	v_cvt_pk_bf16_f32 v39, v41, v42
	s_waitcnt lgkmcnt(3)
	v_mfma_f32_32x32x16_bf16 v[16:31], v[192:195], v[196:199], v[16:31]
	v_cvt_pk_bf16_f32 v192, v76, v79
	v_cvt_pk_bf16_f32 v193, v132, v135
	v_cvt_pk_bf16_f32 v194, v138, v140
	v_cvt_pk_bf16_f32 v195, v153, v184
	v_cvt_pk_bf16_f32 v138, v128, v131
	v_cvt_pk_bf16_f32 v140, v141, v143
	v_cvt_pk_bf16_f32 v141, v185, v188
	s_waitcnt lgkmcnt(1)
	v_mfma_f32_32x32x16_bf16 v[0:15], v[200:203], v[196:199], v[0:15]
	ds_read_b64_tr_b16 v[196:197], v190 offset:40960
	ds_read_b64_tr_b16 v[198:199], v190 offset:41984
	ds_read_b64_tr_b16 v[200:201], v187 offset:40960
	ds_read_b64_tr_b16 v[202:203], v187 offset:41984
	v_cvt_pk_bf16_f32 v36, v35, v36
	s_waitcnt lgkmcnt(4)
	v_add_f32_e32 v32, v32, v33
	v_add_f32_e32 v32, v34, v32
	s_waitcnt lgkmcnt(2)
	v_mfma_f32_32x32x16_bf16 v[16:31], v[196:199], v[192:195], v[16:31]
	s_waitcnt lgkmcnt(0)
	v_mfma_f32_32x32x16_bf16 v[0:15], v[200:203], v[192:195], v[0:15]
	ds_read_b64_tr_b16 v[192:193], v190 offset:43008
	ds_read_b64_tr_b16 v[194:195], v190 offset:44032
	ds_read_b64_tr_b16 v[196:197], v187 offset:43008
	ds_read_b64_tr_b16 v[198:199], v187 offset:44032
	s_waitcnt lgkmcnt(2)
	v_mfma_f32_32x32x16_bf16 v[16:31], v[192:195], v[138:141], v[16:31]
	s_waitcnt lgkmcnt(0)
	v_mfma_f32_32x32x16_bf16 v[0:15], v[196:199], v[138:141], v[0:15]
	v_cvt_pk_bf16_f32 v141, v130, v133
	ds_read_b64_tr_b16 v[130:131], v190 offset:45056
	ds_read_b64_tr_b16 v[132:133], v190 offset:46080
	ds_read_b64_tr_b16 v[192:193], v187 offset:45056
	ds_read_b64_tr_b16 v[194:195], v187 offset:46080
	v_cvt_pk_bf16_f32 v138, v64, v66
	v_cvt_pk_bf16_f32 v139, v70, v72
	v_cvt_pk_bf16_f32 v140, v74, v77
	v_cvt_pk_bf16_f32 v74, v78, v129
	v_cvt_pk_bf16_f32 v72, v67, v69
	s_waitcnt lgkmcnt(2)
	v_mfma_f32_32x32x16_bf16 v[16:31], v[130:133], v[138:141], v[16:31]
	ds_read_b64_tr_b16 v[76:77], v190 offset:47104
	ds_read_b64_tr_b16 v[78:79], v190 offset:48128
	ds_read_b64_tr_b16 v[128:129], v187 offset:47104
	ds_read_b64_tr_b16 v[130:131], v187 offset:48128
	s_waitcnt lgkmcnt(4)
	v_mfma_f32_32x32x16_bf16 v[0:15], v[192:195], v[138:141], v[0:15]
	s_waitcnt lgkmcnt(2)
	v_mfma_f32_32x32x16_bf16 v[16:31], v[76:79], v[72:75], v[16:31]
	s_waitcnt lgkmcnt(0)
	v_mfma_f32_32x32x16_bf16 v[0:15], v[128:131], v[72:75], v[0:15]
	v_cvt_pk_bf16_f32 v74, v63, v65
	v_cvt_pk_bf16_f32 v75, v68, v71
	ds_read_b64_tr_b16 v[64:65], v190 offset:49152
	ds_read_b64_tr_b16 v[66:67], v190 offset:50176
	ds_read_b64_tr_b16 v[68:69], v187 offset:49152
	ds_read_b64_tr_b16 v[70:71], v187 offset:50176
	v_cvt_pk_bf16_f32 v72, v51, v52
	v_cvt_pk_bf16_f32 v73, v57, v61
	v_cvt_pk_bf16_f32 v52, v53, v54
	v_cvt_pk_bf16_f32 v53, v55, v56
	s_waitcnt lgkmcnt(2)
	v_mfma_f32_32x32x16_bf16 v[16:31], v[64:67], v[72:75], v[16:31]
	v_cvt_pk_bf16_f32 v54, v58, v59
	v_cvt_pk_bf16_f32 v55, v60, v62
	ds_read_b64_tr_b16 v[56:57], v190 offset:51200
	ds_read_b64_tr_b16 v[58:59], v190 offset:52224
	ds_read_b64_tr_b16 v[60:61], v187 offset:51200
	ds_read_b64_tr_b16 v[62:63], v187 offset:52224
	s_waitcnt lgkmcnt(4)
	v_mfma_f32_32x32x16_bf16 v[0:15], v[68:71], v[72:75], v[0:15]
	s_waitcnt lgkmcnt(2)
	v_mfma_f32_32x32x16_bf16 v[16:31], v[56:59], v[52:55], v[16:31]
	s_waitcnt lgkmcnt(0)
	v_mfma_f32_32x32x16_bf16 v[0:15], v[60:63], v[52:55], v[0:15]
	ds_read_b64_tr_b16 v[48:49], v190 offset:53248
	ds_read_b64_tr_b16 v[50:51], v190 offset:54272
	ds_read_b64_tr_b16 v[52:53], v187 offset:53248
	ds_read_b64_tr_b16 v[54:55], v187 offset:54272
	s_waitcnt lgkmcnt(2)
	v_mfma_f32_32x32x16_bf16 v[16:31], v[48:51], v[44:47], v[16:31]
	s_waitcnt lgkmcnt(0)
	v_mfma_f32_32x32x16_bf16 v[0:15], v[52:55], v[44:47], v[0:15]
	ds_read_b64_tr_b16 v[40:41], v190 offset:55296
	ds_read_b64_tr_b16 v[42:43], v190 offset:56320
	ds_read_b64_tr_b16 v[44:45], v187 offset:55296
	ds_read_b64_tr_b16 v[46:47], v187 offset:56320
	s_waitcnt lgkmcnt(2)
	v_mfma_f32_32x32x16_bf16 v[16:31], v[40:43], v[36:39], v[16:31]
	s_waitcnt lgkmcnt(0)
	v_mfma_f32_32x32x16_bf16 v[0:15], v[44:47], v[36:39], v[0:15]
	s_cbranch_execnz .LBB0_471
	s_branch .LBB0_489

.LBB0_1118:
	s_ashr_i32 s71, s70, 31
	s_lshl_b32 s44, s90, 6
	s_lshl_b64 s[46:47], s[70:71], 25
	s_add_u32 s45, s50, s46
	s_addc_u32 s93, s51, s47
	s_lshl_b64 s[46:47], s[56:57], 10
	s_add_u32 s45, s45, s46
	s_addc_u32 s46, s93, s47
	s_lshl_b32 s44, s44, 1
	s_add_u32 s44, s45, s44
	s_addc_u32 s45, s46, 0
	s_cmp_lg_u32 s92, 0
	v_add_u32_e32 v193, v176, v177
	s_cbranch_scc0 .LBB0_1123
	ds_read_b128 v[0:3], v190
	ds_read_b128 v[4:7], v190 offset:32
	s_movk_i32 s46, 0xff7e
	s_waitcnt lgkmcnt(1)
	v_mfma_f32_32x32x16_bf16 v[64:79], v[0:3], v[156:159], 0
	ds_read_b128 v[0:3], v190 offset:64
	ds_read_b128 v[48:51], v190 offset:13856
	ds_read_b128 v[194:197], v190 offset:18464
	s_waitcnt lgkmcnt(3)
	v_mfma_f32_32x32x16_bf16 v[64:79], v[4:7], v[152:155], v[64:79]
	s_waitcnt lgkmcnt(2)
	v_mfma_f32_32x32x16_bf16 v[64:79], v[0:3], v[148:151], v[64:79]
	ds_read_b128 v[0:3], v190 offset:96
	s_waitcnt lgkmcnt(0)
	v_mfma_f32_32x32x16_bf16 v[64:79], v[0:3], v[144:147], v[64:79]
	ds_read_b128 v[0:3], v190 offset:4608
	s_waitcnt lgkmcnt(0)
	v_mfma_f32_32x32x16_bf16 v[32:47], v[0:3], v[156:159], 0
	ds_read_b128 v[0:3], v190 offset:4640
	s_nop 7
	v_mul_f32_e32 v64, 0x3e38aa3b, v64
	v_mul_f32_e32 v65, 0x3e38aa3b, v65
	v_mul_f32_e32 v66, 0x3e38aa3b, v66
	v_mul_f32_e32 v67, 0x3e38aa3b, v67
	v_mul_f32_e32 v68, 0x3e38aa3b, v68
	v_mul_f32_e32 v69, 0x3e38aa3b, v69
	s_waitcnt lgkmcnt(0)
	v_mfma_f32_32x32x16_bf16 v[32:47], v[0:3], v[152:155], v[32:47]
	ds_read_b128 v[0:3], v190 offset:4672
	v_mul_f32_e32 v70, 0x3e38aa3b, v70
	v_mul_f32_e32 v71, 0x3e38aa3b, v71
	v_mul_f32_e32 v72, 0x3e38aa3b, v72
	v_mul_f32_e32 v73, 0x3e38aa3b, v73
	v_mul_f32_e32 v74, 0x3e38aa3b, v74
	v_mul_f32_e32 v75, 0x3e38aa3b, v75
	s_waitcnt lgkmcnt(0)
	v_mfma_f32_32x32x16_bf16 v[32:47], v[0:3], v[148:151], v[32:47]
	ds_read_b128 v[0:3], v190 offset:4704
	v_mul_f32_e32 v76, 0x3e38aa3b, v76
	v_mul_f32_e32 v77, 0x3e38aa3b, v77
	v_mul_f32_e32 v78, 0x3e38aa3b, v78
	v_mul_f32_e32 v79, 0x3e38aa3b, v79
	s_waitcnt lgkmcnt(0)
	v_mfma_f32_32x32x16_bf16 v[32:47], v[0:3], v[144:147], v[32:47]
	ds_read_b128 v[0:3], v190 offset:9216
	s_waitcnt lgkmcnt(0)
	v_mfma_f32_32x32x16_bf16 v[16:31], v[0:3], v[156:159], 0
	ds_read_b128 v[0:3], v190 offset:9248
	s_nop 7
	v_mul_f32_e32 v198, 0x3e38aa3b, v33
	s_waitcnt lgkmcnt(0)
	v_mfma_f32_32x32x16_bf16 v[16:31], v[0:3], v[152:155], v[16:31]
	ds_read_b128 v[0:3], v190 offset:9280
	s_waitcnt lgkmcnt(0)
	v_mfma_f32_32x32x16_bf16 v[16:31], v[0:3], v[148:151], v[16:31]
	ds_read_b128 v[0:3], v190 offset:9312
	s_waitcnt lgkmcnt(0)
	v_mfma_f32_32x32x16_bf16 v[16:31], v[0:3], v[144:147], v[16:31]
	ds_read_b128 v[0:3], v190 offset:13824
	s_waitcnt lgkmcnt(0)
	v_mfma_f32_32x32x16_bf16 v[0:15], v[0:3], v[156:159], 0
	v_mfma_f32_32x32x16_bf16 v[0:15], v[48:51], v[152:155], v[0:15]
	ds_read_b128 v[48:51], v190 offset:13888
	s_waitcnt lgkmcnt(0)
	v_mfma_f32_32x32x16_bf16 v[0:15], v[48:51], v[148:151], v[0:15]
	ds_read_b128 v[48:51], v190 offset:13920
	s_waitcnt lgkmcnt(0)
	v_mfma_f32_32x32x16_bf16 v[0:15], v[48:51], v[144:147], v[0:15]
	ds_read_b128 v[48:51], v190 offset:18432
	s_waitcnt lgkmcnt(0)
	v_mfma_f32_32x32x16_bf16 v[48:63], v[48:51], v[156:159], 0
	v_mfma_f32_32x32x16_bf16 v[48:63], v[194:197], v[152:155], v[48:63]
	ds_read_b128 v[194:197], v190 offset:18496
	s_waitcnt lgkmcnt(0)
	v_mfma_f32_32x32x16_bf16 v[48:63], v[194:197], v[148:151], v[48:63]
	ds_read_b128 v[194:197], v190 offset:18528
	s_waitcnt lgkmcnt(0)
	v_mfma_f32_32x32x16_bf16 v[48:63], v[194:197], v[144:147], v[48:63]
	v_or_b32_e32 v194, s54, v162
	v_add_u32_e32 v195, s91, v175
	v_sub_u32_e32 v196, v194, v195
	v_cmp_gt_i32_e32 vcc, s81, v196
	v_sub_u32_e32 v197, v195, v194
	s_nop 6
	v_mul_f32_e32 v48, 0x3e38aa3b, v48
	v_cndmask_b32_e32 v64, v191, v64, vcc
	v_cmp_lt_i32_e32 vcc, s46, v197
	s_movk_i32 s46, 0x83
	v_mul_f32_e32 v49, 0x3e38aa3b, v49
	v_cndmask_b32_e32 v65, v191, v65, vcc
	v_cmp_gt_i32_e32 vcc, s46, v196
	s_movk_i32 s46, 0x84
	v_max3_f32 v197, v64, s87, v65
	v_cndmask_b32_e32 v66, v191, v66, vcc
	v_cmp_gt_i32_e32 vcc, s46, v196
	s_movk_i32 s46, 0x89
	v_mul_f32_e32 v50, 0x3e38aa3b, v50
	v_cndmask_b32_e32 v67, v191, v67, vcc
	v_cmp_gt_i32_e32 vcc, s46, v196
	s_movk_i32 s46, 0x8a
	v_max3_f32 v197, v197, v66, v67
	v_cndmask_b32_e32 v68, v191, v68, vcc
	v_cmp_gt_i32_e32 vcc, s46, v196
	s_movk_i32 s46, 0x8b
	v_mul_f32_e32 v51, 0x3e38aa3b, v51
	v_cndmask_b32_e32 v69, v191, v69, vcc
	v_cmp_gt_i32_e32 vcc, s46, v196
	s_movk_i32 s46, 0x8c
	v_max3_f32 v197, v197, v68, v69
	v_cndmask_b32_e32 v70, v191, v70, vcc
	v_cmp_gt_i32_e32 vcc, s46, v196
	s_movk_i32 s46, 0x91
	v_mul_f32_e32 v52, 0x3e38aa3b, v52
	v_cndmask_b32_e32 v71, v191, v71, vcc
	v_cmp_gt_i32_e32 vcc, s46, v196
	s_movk_i32 s46, 0x92
	v_max3_f32 v197, v197, v70, v71
	v_cndmask_b32_e32 v72, v191, v72, vcc
	v_cmp_gt_i32_e32 vcc, s46, v196
	s_movk_i32 s46, 0x93
	s_nop 0
	v_cndmask_b32_e32 v73, v191, v73, vcc
	v_cmp_gt_i32_e32 vcc, s46, v196
	s_movk_i32 s46, 0x94
	v_max3_f32 v197, v197, v72, v73
	v_cndmask_b32_e32 v74, v191, v74, vcc
	v_cmp_gt_i32_e32 vcc, s46, v196
	s_movk_i32 s46, 0x99
	s_nop 0
	v_cndmask_b32_e32 v75, v191, v75, vcc
	v_cmp_gt_i32_e32 vcc, s46, v196
	s_movk_i32 s46, 0x9a
	v_max3_f32 v197, v197, v74, v75
	v_cndmask_b32_e32 v76, v191, v76, vcc
	v_cmp_gt_i32_e32 vcc, s46, v196
	s_movk_i32 s46, 0x9b
	s_nop 0
	v_cndmask_b32_e32 v77, v191, v77, vcc
	v_cmp_gt_i32_e32 vcc, s46, v196
	s_movk_i32 s46, 0x9c
	v_max3_f32 v197, v197, v76, v77
	v_cndmask_b32_e32 v78, v191, v78, vcc
	v_cmp_gt_i32_e32 vcc, s46, v196
	s_nop 1
	v_cndmask_b32_e32 v79, v191, v79, vcc
	v_max3_f32 v196, v197, v78, v79
	v_mul_f32_e32 v197, 0x3e38aa3b, v32
	v_max3_f32 v196, v196, v197, v198
	v_max_f32_e32 v197, v34, v35
	v_max3_f32 v197, v197, v36, v37
	v_max3_f32 v197, v197, v38, v39
	v_max3_f32 v197, v197, v40, v41
	v_max3_f32 v197, v197, v42, v43
	v_max3_f32 v197, v197, v44, v45
	v_max3_f32 v197, v197, v46, v47
	v_max3_f32 v197, v197, v16, v17
	v_max3_f32 v197, v197, v18, v19
	v_max3_f32 v197, v197, v20, v21
	v_max3_f32 v197, v197, v22, v23
	v_max3_f32 v197, v197, v24, v25
	v_max3_f32 v197, v197, v26, v27
	v_max3_f32 v197, v197, v28, v29
	v_max3_f32 v197, v197, v30, v31
	v_max3_f32 v197, v197, v0, v1
	v_max3_f32 v197, v197, v2, v3
	v_max3_f32 v197, v197, v4, v5
	v_max3_f32 v197, v197, v6, v7
	v_max3_f32 v197, v197, v8, v9
	v_max3_f32 v197, v197, v10, v11
	v_max3_f32 v197, v197, v12, v13
	v_max3_f32 v197, v197, v14, v15
	v_mul_f32_e32 v197, 0x3e38aa3b, v197
	v_max_f32_e32 v196, v196, v197
	v_add_u32_e32 v197, 0x80, v195
	v_cmp_ge_i32_e32 vcc, v194, v197
	s_nop 1
	v_cndmask_b32_e32 v229, v191, v48, vcc
	v_add_u32_e32 v48, 0x81, v195
	v_cmp_ge_i32_e32 vcc, v194, v48
	s_nop 1
	v_cndmask_b32_e32 v49, v191, v49, vcc
	v_max3_f32 v48, v196, v229, v49
	v_add_u32_e32 v196, 0x82, v195
	v_cmp_ge_i32_e32 vcc, v194, v196
	v_add_u32_e32 v196, 0x83, v195
	s_nop 0
	v_cndmask_b32_e32 v50, v191, v50, vcc
	v_cmp_ge_i32_e32 vcc, v194, v196
	s_nop 1
	v_cndmask_b32_e32 v230, v191, v51, vcc
	v_add_u32_e32 v51, 0x88, v195
	v_cmp_ge_i32_e32 vcc, v194, v51
	v_add_u32_e32 v51, 0x89, v195
	v_max3_f32 v48, v48, v50, v230
	v_cndmask_b32_e32 v231, v191, v52, vcc
	v_mul_f32_e32 v52, 0x3e38aa3b, v53
	v_cmp_ge_i32_e32 vcc, v194, v51
	v_add_u32_e32 v51, 0x8a, v195
	s_nop 0
	v_cndmask_b32_e32 v232, v191, v52, vcc
	v_mul_f32_e32 v52, 0x3e38aa3b, v54
	v_cmp_ge_i32_e32 vcc, v194, v51
	v_add_u32_e32 v51, 0x8b, v195
	v_max3_f32 v48, v48, v231, v232
	v_cndmask_b32_e32 v233, v191, v52, vcc
	v_mul_f32_e32 v52, 0x3e38aa3b, v55
	v_cmp_ge_i32_e32 vcc, v194, v51
	v_add_u32_e32 v51, 0x90, v195
	s_nop 0
	v_cndmask_b32_e32 v234, v191, v52, vcc
	v_mul_f32_e32 v52, 0x3e38aa3b, v56
	v_cmp_ge_i32_e32 vcc, v194, v51
	v_add_u32_e32 v51, 0x91, v195
	v_max3_f32 v48, v48, v233, v234
	v_cndmask_b32_e32 v235, v191, v52, vcc
	v_mul_f32_e32 v52, 0x3e38aa3b, v57
	v_cmp_ge_i32_e32 vcc, v194, v51
	v_add_u32_e32 v51, 0x92, v195
	s_nop 0
	v_cndmask_b32_e32 v236, v191, v52, vcc
	v_mul_f32_e32 v52, 0x3e38aa3b, v58
	v_cmp_ge_i32_e32 vcc, v194, v51
	v_add_u32_e32 v51, 0x93, v195
	v_max3_f32 v48, v48, v235, v236
	v_cndmask_b32_e32 v237, v191, v52, vcc
	v_mul_f32_e32 v52, 0x3e38aa3b, v59
	v_cmp_ge_i32_e32 vcc, v194, v51
	v_add_u32_e32 v51, 0x98, v195
	s_nop 0
	v_cndmask_b32_e32 v238, v191, v52, vcc
	v_mul_f32_e32 v52, 0x3e38aa3b, v60
	v_cmp_ge_i32_e32 vcc, v194, v51
	v_add_u32_e32 v51, 0x99, v195
	v_max3_f32 v48, v48, v237, v238
	v_cndmask_b32_e32 v239, v191, v52, vcc
	v_mul_f32_e32 v52, 0x3e38aa3b, v61
	v_cmp_ge_i32_e32 vcc, v194, v51
	v_add_u32_e32 v51, 0x9a, v195
	s_nop 0
	v_cndmask_b32_e32 v240, v191, v52, vcc
	v_mul_f32_e32 v52, 0x3e38aa3b, v62
	v_cmp_ge_i32_e32 vcc, v194, v51
	v_add_u32_e32 v51, 0x9b, v195
	v_max3_f32 v48, v48, v239, v240
	v_cndmask_b32_e32 v241, v191, v52, vcc
	v_mul_f32_e32 v52, 0x3e38aa3b, v63
	v_cmp_ge_i32_e32 vcc, v194, v51
	v_xor_b32_e32 v51, 32, v192
	s_nop 0
	v_cndmask_b32_e32 v242, v191, v52, vcc
	v_and_b32_e32 v52, 64, v192
	v_add_u32_e32 v52, 64, v52
	v_cmp_lt_i32_e32 vcc, v51, v52
	v_max3_f32 v48, v48, v241, v242
	s_nop 0
	v_cndmask_b32_e32 v51, v192, v51, vcc
	v_lshlrev_b32_e32 v243, 2, v51
	ds_bpermute_b32 v51, v243, v48
	s_waitcnt lgkmcnt(0)
	v_max_f32_e32 v51, v51, v51
	v_max_f32_e32 v48, v48, v51
	v_sub_f32_e32 v51, v64, v48
	v_exp_f32_e32 v209, v51
	v_sub_f32_e32 v52, v65, v48
	v_exp_f32_e32 v222, v52
	v_sub_f32_e32 v52, v66, v48
	v_exp_f32_e32 v223, v52
	v_sub_f32_e32 v52, v67, v48
	v_exp_f32_e32 v224, v52
	v_sub_f32_e32 v52, v68, v48
	v_add_f32_e32 v51, 0, v209
	v_exp_f32_e32 v225, v52
	v_sub_f32_e32 v52, v69, v48
	v_add_f32_e32 v51, v222, v51
	v_exp_f32_e32 v226, v52
	v_sub_f32_e32 v52, v70, v48
	v_add_f32_e32 v51, v223, v51
	v_exp_f32_e32 v227, v52
	v_sub_f32_e32 v52, v71, v48
	v_add_f32_e32 v51, v224, v51
	v_exp_f32_e32 v228, v52
	v_sub_f32_e32 v52, v72, v48
	v_add_f32_e32 v51, v225, v51
	v_exp_f32_e32 v210, v52
	v_sub_f32_e32 v52, v73, v48
	v_add_f32_e32 v51, v226, v51
	v_exp_f32_e32 v213, v52
	v_sub_f32_e32 v52, v74, v48
	v_add_f32_e32 v51, v227, v51
	v_exp_f32_e32 v215, v52
	v_sub_f32_e32 v52, v75, v48
	v_add_f32_e32 v51, v228, v51
	v_exp_f32_e32 v217, v52
	v_sub_f32_e32 v52, v76, v48
	v_add_f32_e32 v51, v210, v51
	v_exp_f32_e32 v218, v52
	v_sub_f32_e32 v52, v77, v48
	v_add_f32_e32 v51, v213, v51
	v_exp_f32_e32 v219, v52
	v_sub_f32_e32 v52, v78, v48
	v_add_f32_e32 v51, v215, v51
	v_exp_f32_e32 v220, v52
	v_sub_f32_e32 v52, v79, v48
	v_add_f32_e32 v51, v217, v51
	v_exp_f32_e32 v221, v52
	v_fma_f32 v32, v32, s86, -v48
	v_add_f32_e32 v51, v218, v51
	v_exp_f32_e32 v76, v32
	v_fma_f32 v33, v33, s86, -v48
	v_add_f32_e32 v51, v219, v51
	v_exp_f32_e32 v194, v33
	v_fma_f32 v33, v34, s86, -v48
	v_add_f32_e32 v51, v220, v51
	v_exp_f32_e32 v197, v33
	v_fma_f32 v33, v35, s86, -v48
	v_add_f32_e32 v51, v221, v51
	v_exp_f32_e32 v201, v33
	v_fma_f32 v33, v36, s86, -v48
	v_add_f32_e32 v32, v76, v51
	v_exp_f32_e32 v205, v33
	v_fma_f32 v33, v37, s86, -v48
	v_add_f32_e32 v32, v194, v32
	v_exp_f32_e32 v206, v33
	v_fma_f32 v33, v38, s86, -v48
	v_add_f32_e32 v32, v197, v32
	v_exp_f32_e32 v208, v33
	v_fma_f32 v33, v39, s86, -v48
	v_add_f32_e32 v32, v201, v32
	v_exp_f32_e32 v212, v33
	v_fma_f32 v33, v40, s86, -v48
	v_add_f32_e32 v32, v205, v32
	v_exp_f32_e32 v195, v33
	v_fma_f32 v33, v41, s86, -v48
	v_add_f32_e32 v32, v206, v32
	v_exp_f32_e32 v200, v33
	v_fma_f32 v33, v42, s86, -v48
	v_add_f32_e32 v32, v208, v32
	v_exp_f32_e32 v202, v33
	v_fma_f32 v33, v43, s86, -v48
	v_add_f32_e32 v32, v212, v32
	v_exp_f32_e32 v204, v33
	v_fma_f32 v33, v44, s86, -v48
	v_add_f32_e32 v32, v195, v32
	v_exp_f32_e32 v207, v33
	v_fma_f32 v33, v45, s86, -v48
	v_add_f32_e32 v32, v200, v32
	v_exp_f32_e32 v211, v33
	v_fma_f32 v33, v46, s86, -v48
	v_add_f32_e32 v32, v202, v32
	v_exp_f32_e32 v214, v33
	v_fma_f32 v33, v47, s86, -v48
	v_add_f32_e32 v32, v204, v32
	v_exp_f32_e32 v216, v33
	v_fma_f32 v16, v16, s86, -v48
	v_add_f32_e32 v32, v207, v32
	v_exp_f32_e32 v64, v16
	v_fma_f32 v17, v17, s86, -v48
	v_add_f32_e32 v32, v211, v32
	v_exp_f32_e32 v67, v17
	v_fma_f32 v17, v18, s86, -v48
	v_add_f32_e32 v32, v214, v32
	v_exp_f32_e32 v69, v17
	v_fma_f32 v17, v19, s86, -v48
	v_add_f32_e32 v32, v216, v32
	v_exp_f32_e32 v72, v17
	v_fma_f32 v17, v20, s86, -v48
	v_add_f32_e32 v16, v64, v32
	v_exp_f32_e32 v75, v17
	v_fma_f32 v17, v21, s86, -v48
	v_add_f32_e32 v16, v67, v16
	v_exp_f32_e32 v77, v17
	v_fma_f32 v17, v22, s86, -v48
	v_add_f32_e32 v16, v69, v16
	v_exp_f32_e32 v79, v17
	v_fma_f32 v17, v23, s86, -v48
	v_add_f32_e32 v16, v72, v16
	v_exp_f32_e32 v198, v17
	v_fma_f32 v17, v24, s86, -v48
	v_add_f32_e32 v16, v75, v16
	v_exp_f32_e32 v68, v17
	v_fma_f32 v17, v25, s86, -v48
	v_add_f32_e32 v16, v77, v16
	v_exp_f32_e32 v71, v17
	v_fma_f32 v17, v26, s86, -v48
	v_add_f32_e32 v16, v79, v16
	v_exp_f32_e32 v73, v17
	v_fma_f32 v17, v27, s86, -v48
	v_add_f32_e32 v16, v198, v16
	v_exp_f32_e32 v74, v17
	v_fma_f32 v17, v28, s86, -v48
	v_add_f32_e32 v16, v68, v16
	v_exp_f32_e32 v78, v17
	v_fma_f32 v17, v29, s86, -v48
	v_add_f32_e32 v16, v71, v16
	v_exp_f32_e32 v196, v17
	v_fma_f32 v17, v30, s86, -v48
	v_add_f32_e32 v16, v73, v16
	v_exp_f32_e32 v199, v17
	v_fma_f32 v17, v31, s86, -v48
	v_add_f32_e32 v16, v74, v16
	v_exp_f32_e32 v203, v17
	v_fma_f32 v0, v0, s86, -v48
	v_add_f32_e32 v16, v78, v16
	v_exp_f32_e32 v51, v0
	v_fma_f32 v1, v1, s86, -v48
	v_add_f32_e32 v16, v196, v16
	v_exp_f32_e32 v52, v1
	v_fma_f32 v1, v2, s86, -v48
	v_add_f32_e32 v16, v199, v16
	v_exp_f32_e32 v54, v1
	v_fma_f32 v1, v3, s86, -v48
	v_add_f32_e32 v16, v203, v16
	v_exp_f32_e32 v57, v1
	v_fma_f32 v1, v4, s86, -v48
	v_add_f32_e32 v0, v51, v16
	v_exp_f32_e32 v63, v1
	v_fma_f32 v1, v5, s86, -v48
	v_add_f32_e32 v0, v52, v0
	v_exp_f32_e32 v65, v1
	v_fma_f32 v1, v6, s86, -v48
	v_add_f32_e32 v0, v54, v0
	v_exp_f32_e32 v66, v1
	v_fma_f32 v1, v7, s86, -v48
	v_add_f32_e32 v0, v57, v0
	v_exp_f32_e32 v70, v1
	v_fma_f32 v1, v8, s86, -v48
	v_add_f32_e32 v0, v63, v0
	v_exp_f32_e32 v53, v1
	v_fma_f32 v1, v9, s86, -v48
	v_add_f32_e32 v0, v65, v0
	v_exp_f32_e32 v55, v1
	v_fma_f32 v1, v10, s86, -v48
	v_add_f32_e32 v0, v66, v0
	v_exp_f32_e32 v56, v1
	v_fma_f32 v1, v11, s86, -v48
	v_add_f32_e32 v0, v70, v0
	v_exp_f32_e32 v58, v1
	v_fma_f32 v1, v12, s86, -v48
	v_add_f32_e32 v0, v53, v0
	v_exp_f32_e32 v59, v1
	v_fma_f32 v1, v13, s86, -v48
	v_add_f32_e32 v0, v55, v0
	v_exp_f32_e32 v60, v1
	v_fma_f32 v1, v14, s86, -v48
	v_add_f32_e32 v0, v56, v0
	v_exp_f32_e32 v61, v1
	v_fma_f32 v1, v15, s86, -v48
	v_add_f32_e32 v0, v58, v0
	v_exp_f32_e32 v62, v1
	v_sub_f32_e32 v1, v229, v48
	v_add_f32_e32 v0, v59, v0
	v_exp_f32_e32 v42, v1
	v_sub_f32_e32 v1, v49, v48
	v_add_f32_e32 v0, v60, v0
	v_exp_f32_e32 v43, v1
	v_sub_f32_e32 v1, v50, v48
	v_add_f32_e32 v0, v61, v0
	v_exp_f32_e32 v44, v1
	v_sub_f32_e32 v1, v230, v48
	v_add_f32_e32 v0, v62, v0
	v_exp_f32_e32 v45, v1
	v_sub_f32_e32 v1, v231, v48
	v_add_f32_e32 v0, v42, v0
	v_exp_f32_e32 v46, v1
	v_sub_f32_e32 v1, v232, v48
	v_add_f32_e32 v0, v43, v0
	v_exp_f32_e32 v47, v1
	v_sub_f32_e32 v1, v233, v48
	v_add_f32_e32 v0, v44, v0
	v_exp_f32_e32 v49, v1
	v_sub_f32_e32 v1, v234, v48
	v_add_f32_e32 v0, v45, v0
	v_exp_f32_e32 v50, v1
	v_sub_f32_e32 v1, v235, v48
	v_add_f32_e32 v0, v46, v0
	v_exp_f32_e32 v34, v1
	v_sub_f32_e32 v1, v236, v48
	v_add_f32_e32 v0, v47, v0
	v_exp_f32_e32 v35, v1
	v_sub_f32_e32 v1, v237, v48
	v_add_f32_e32 v0, v49, v0
	v_exp_f32_e32 v36, v1
	v_sub_f32_e32 v1, v238, v48
	v_add_f32_e32 v0, v50, v0
	v_exp_f32_e32 v37, v1
	v_sub_f32_e32 v1, v239, v48
	v_add_f32_e32 v0, v34, v0
	v_exp_f32_e32 v38, v1
	v_sub_f32_e32 v1, v240, v48
	v_add_f32_e32 v0, v35, v0
	v_exp_f32_e32 v39, v1
	v_sub_f32_e32 v1, v241, v48
	v_add_f32_e32 v0, v36, v0
	v_exp_f32_e32 v40, v1
	v_sub_f32_e32 v1, v242, v48
	v_add_f32_e32 v0, v37, v0
	v_exp_f32_e32 v41, v1
	v_add_f32_e32 v0, v38, v0
	v_add_f32_e32 v0, v39, v0
	v_add_f32_e32 v0, v40, v0
	v_add_f32_e32 v32, v41, v0
	v_cvt_pk_bf16_f32 v0, v209, v222
	v_add_u32_e32 v209, v176, v178
	ds_read_b64_tr_b16 v[4:5], v193 offset:36864
	ds_read_b64_tr_b16 v[6:7], v193 offset:37888
	ds_read_b64_tr_b16 v[8:9], v209 offset:36864
	ds_read_b64_tr_b16 v[10:11], v209 offset:37888
	v_cvt_pk_bf16_f32 v1, v223, v224
	v_cvt_pk_bf16_f32 v2, v225, v226
	v_cvt_pk_bf16_f32 v3, v227, v228
	v_cvt_pk_bf16_f32 v224, v218, v219
	v_cvt_pk_bf16_f32 v225, v220, v221
	s_waitcnt lgkmcnt(2)
	v_mfma_f32_32x32x16_bf16 v[16:31], v[4:7], v[0:3], 0
	ds_read_b64_tr_b16 v[218:219], v193 offset:38912
	ds_read_b64_tr_b16 v[220:221], v193 offset:39936
	ds_read_b64_tr_b16 v[226:227], v209 offset:38912
	ds_read_b64_tr_b16 v[228:229], v209 offset:39936
	v_cvt_pk_bf16_f32 v222, v210, v213
	v_cvt_pk_bf16_f32 v223, v215, v217
	v_cvt_pk_bf16_f32 v73, v73, v74
	v_cvt_pk_bf16_f32 v74, v78, v196
	v_cvt_pk_bf16_f32 v42, v42, v43
	v_cvt_pk_bf16_f32 v43, v44, v45
	s_waitcnt lgkmcnt(4)
	v_mfma_f32_32x32x16_bf16 v[0:15], v[8:11], v[0:3], 0
	v_cvt_pk_bf16_f32 v45, v49, v50
	v_cvt_pk_bf16_f32 v44, v46, v47
	ds_bpermute_b32 v33, v243, v32
	v_cvt_pk_bf16_f32 v34, v34, v35
	v_cvt_pk_bf16_f32 v35, v36, v37
	v_cvt_pk_bf16_f32 v36, v38, v39
	v_cvt_pk_bf16_f32 v37, v40, v41
	s_waitcnt lgkmcnt(3)
	v_mfma_f32_32x32x16_bf16 v[16:31], v[218:221], v[222:225], v[16:31]
	v_cvt_pk_bf16_f32 v218, v76, v194
	v_cvt_pk_bf16_f32 v219, v197, v201
	v_cvt_pk_bf16_f32 v220, v205, v206
	v_cvt_pk_bf16_f32 v221, v208, v212
	s_waitcnt lgkmcnt(0)
	v_add_f32_e32 v32, v32, v33
	v_div_scale_f32 v33, s[46:47], v32, v32, 1.0
	v_mfma_f32_32x32x16_bf16 v[0:15], v[226:229], v[222:225], v[0:15]
	ds_read_b64_tr_b16 v[222:223], v193 offset:40960
	ds_read_b64_tr_b16 v[224:225], v193 offset:41984
	ds_read_b64_tr_b16 v[226:227], v209 offset:40960
	ds_read_b64_tr_b16 v[228:229], v209 offset:41984
	s_add_i32 s46, s89, 9
	s_waitcnt lgkmcnt(2)
	v_mfma_f32_32x32x16_bf16 v[16:31], v[222:225], v[218:221], v[16:31]
	s_waitcnt lgkmcnt(0)
	v_mfma_f32_32x32x16_bf16 v[0:15], v[226:229], v[218:221], v[0:15]
	v_cvt_pk_bf16_f32 v219, v202, v204
	v_cvt_pk_bf16_f32 v220, v207, v211
	ds_read_b64_tr_b16 v[204:205], v193 offset:43008
	ds_read_b64_tr_b16 v[206:207], v193 offset:44032
	ds_read_b64_tr_b16 v[210:211], v209 offset:43008
	ds_read_b64_tr_b16 v[212:213], v209 offset:44032
	v_cvt_pk_bf16_f32 v218, v195, v200
	v_cvt_pk_bf16_f32 v221, v214, v216
	s_waitcnt lgkmcnt(2)
	s_nop 0
	v_mfma_f32_32x32x16_bf16 v[16:31], v[204:207], v[218:221], v[16:31]
	v_cvt_pk_bf16_f32 v204, v64, v67
	v_cvt_pk_bf16_f32 v205, v69, v72
	v_cvt_pk_bf16_f32 v206, v75, v77
	v_cvt_pk_bf16_f32 v207, v79, v198
	v_cvt_pk_bf16_f32 v72, v68, v71
	v_cvt_pk_bf16_f32 v75, v199, v203
	s_waitcnt lgkmcnt(0)
	v_mfma_f32_32x32x16_bf16 v[0:15], v[210:213], v[218:221], v[0:15]
	ds_read_b64_tr_b16 v[210:211], v193 offset:45056
	ds_read_b64_tr_b16 v[212:213], v193 offset:46080
	ds_read_b64_tr_b16 v[214:215], v209 offset:45056
	ds_read_b64_tr_b16 v[216:217], v209 offset:46080
	ds_read_b64_tr_b16 v[76:77], v193 offset:47104
	ds_read_b64_tr_b16 v[78:79], v193 offset:48128
	ds_read_b64_tr_b16 v[194:195], v209 offset:47104
	ds_read_b64_tr_b16 v[196:197], v209 offset:48128
	s_waitcnt lgkmcnt(6)
	v_mfma_f32_32x32x16_bf16 v[16:31], v[210:213], v[204:207], v[16:31]
	s_waitcnt lgkmcnt(4)
	v_mfma_f32_32x32x16_bf16 v[0:15], v[214:217], v[204:207], v[0:15]
	s_waitcnt lgkmcnt(2)
	v_mfma_f32_32x32x16_bf16 v[16:31], v[76:79], v[72:75], v[16:31]
	s_waitcnt lgkmcnt(0)
	v_mfma_f32_32x32x16_bf16 v[0:15], v[194:197], v[72:75], v[0:15]
	v_cvt_pk_bf16_f32 v74, v63, v65
	v_cvt_pk_bf16_f32 v75, v66, v70
	ds_read_b64_tr_b16 v[64:65], v193 offset:49152
	ds_read_b64_tr_b16 v[66:67], v193 offset:50176
	ds_read_b64_tr_b16 v[68:69], v209 offset:49152
	ds_read_b64_tr_b16 v[70:71], v209 offset:50176
	v_cvt_pk_bf16_f32 v72, v51, v52
	v_cvt_pk_bf16_f32 v73, v54, v57
	v_cvt_pk_bf16_f32 v52, v53, v55
	v_cvt_pk_bf16_f32 v53, v56, v58
	s_waitcnt lgkmcnt(2)
	v_mfma_f32_32x32x16_bf16 v[16:31], v[64:67], v[72:75], v[16:31]
	v_cvt_pk_bf16_f32 v54, v59, v60
	v_cvt_pk_bf16_f32 v55, v61, v62
	ds_read_b64_tr_b16 v[56:57], v193 offset:51200
	ds_read_b64_tr_b16 v[58:59], v193 offset:52224
	ds_read_b64_tr_b16 v[60:61], v209 offset:51200
	ds_read_b64_tr_b16 v[62:63], v209 offset:52224
	s_waitcnt lgkmcnt(4)
	v_mfma_f32_32x32x16_bf16 v[0:15], v[68:71], v[72:75], v[0:15]
	s_waitcnt lgkmcnt(2)
	v_mfma_f32_32x32x16_bf16 v[16:31], v[56:59], v[52:55], v[16:31]
	s_waitcnt lgkmcnt(0)
	v_mfma_f32_32x32x16_bf16 v[0:15], v[60:63], v[52:55], v[0:15]
	ds_read_b64_tr_b16 v[50:51], v193 offset:53248
	ds_read_b64_tr_b16 v[52:53], v193 offset:54272
	ds_read_b64_tr_b16 v[54:55], v209 offset:53248
	ds_read_b64_tr_b16 v[56:57], v209 offset:54272
	s_waitcnt lgkmcnt(2)
	v_mfma_f32_32x32x16_bf16 v[16:31], v[50:53], v[42:45], v[16:31]
	s_waitcnt lgkmcnt(0)
	v_mfma_f32_32x32x16_bf16 v[0:15], v[54:57], v[42:45], v[0:15]
	ds_read_b64_tr_b16 v[38:39], v193 offset:55296
	ds_read_b64_tr_b16 v[40:41], v193 offset:56320
	ds_read_b64_tr_b16 v[42:43], v209 offset:55296
	ds_read_b64_tr_b16 v[44:45], v209 offset:56320
	s_waitcnt lgkmcnt(2)
	v_mfma_f32_32x32x16_bf16 v[16:31], v[38:41], v[34:37], v[16:31]
	v_lshlrev_b32_e32 v38, 1, v166
	v_mov_b32_e32 v39, v161
	s_waitcnt lgkmcnt(0)
	v_mfma_f32_32x32x16_bf16 v[0:15], v[42:45], v[34:37], v[0:15]
	v_rcp_f32_e32 v34, v33
	s_nop 0
	v_fma_f32 v35, -v33, v34, 1.0
	v_fmac_f32_e32 v34, v35, v34
	v_div_scale_f32 v35, vcc, 1.0, v32, 1.0
	v_mul_f32_e32 v36, v35, v34
	v_fma_f32 v37, -v33, v36, v35
	v_fmac_f32_e32 v36, v37, v34
	v_fma_f32 v33, -v33, v36, v35
	v_div_fmas_f32 v33, v33, v34, v36
	v_div_fixup_f32 v34, v33, v32, 1.0
	v_lshlrev_b64 v[36:37], s46, v[162:163]
	v_lshl_add_u64 v[36:37], v[36:37], 1, s[44:45]
	v_pk_mul_f32 v[16:17], v[16:17], v[34:35] op_sel_hi:[1,0]
	v_pk_mul_f32 v[18:19], v[18:19], v[34:35] op_sel_hi:[1,0]
	v_pk_mul_f32 v[20:21], v[20:21], v[34:35] op_sel_hi:[1,0]
	v_pk_mul_f32 v[22:23], v[22:23], v[34:35] op_sel_hi:[1,0]
	v_pk_mul_f32 v[24:25], v[24:25], v[34:35] op_sel_hi:[1,0]
	v_pk_mul_f32 v[26:27], v[26:27], v[34:35] op_sel_hi:[1,0]
	v_pk_mul_f32 v[28:29], v[28:29], v[34:35] op_sel_hi:[1,0]
	v_pk_mul_f32 v[30:31], v[30:31], v[34:35] op_sel_hi:[1,0]
	v_pk_mul_f32 v[0:1], v[0:1], v[34:35] op_sel_hi:[1,0]
	v_pk_mul_f32 v[2:3], v[2:3], v[34:35] op_sel_hi:[1,0]
	v_pk_mul_f32 v[4:5], v[4:5], v[34:35] op_sel_hi:[1,0]
	v_pk_mul_f32 v[6:7], v[6:7], v[34:35] op_sel_hi:[1,0]
	v_pk_mul_f32 v[8:9], v[8:9], v[34:35] op_sel_hi:[1,0]
	v_pk_mul_f32 v[10:11], v[10:11], v[34:35] op_sel_hi:[1,0]
	v_pk_mul_f32 v[12:13], v[12:13], v[34:35] op_sel_hi:[1,0]
	v_pk_mul_f32 v[14:15], v[14:15], v[34:35] op_sel_hi:[1,0]
	v_lshl_add_u64 v[36:37], v[36:37], 0, v[38:39]
	v_lshl_add_u64 v[36:37], v[36:37], 0, v[38:39]
	v_cvt_pk_bf16_f32 v16, v16, v17
	v_cvt_pk_bf16_f32 v17, v18, v19
	v_cvt_pk_bf16_f32 v18, v20, v21
	v_cvt_pk_bf16_f32 v19, v22, v23
	v_cvt_pk_bf16_f32 v20, v24, v25
	v_cvt_pk_bf16_f32 v21, v26, v27
	v_cvt_pk_bf16_f32 v22, v28, v29
	v_cvt_pk_bf16_f32 v23, v30, v31
	v_cvt_pk_bf16_f32 v0, v0, v1
	v_cvt_pk_bf16_f32 v1, v2, v3
	v_cvt_pk_bf16_f32 v2, v4, v5
	v_cvt_pk_bf16_f32 v3, v6, v7
	v_cvt_pk_bf16_f32 v4, v8, v9
	v_cvt_pk_bf16_f32 v5, v10, v11
	v_cvt_pk_bf16_f32 v6, v12, v13
	v_cvt_pk_bf16_f32 v7, v14, v15
	s_nop 1
	v_permlane32_swap_b32 v16, v18
	v_permlane32_swap_b32 v17, v19
	v_permlane32_swap_b32 v20, v22
	v_permlane32_swap_b32 v21, v23
	v_permlane32_swap_b32 v0, v2
	v_permlane32_swap_b32 v1, v3
	v_permlane32_swap_b32 v4, v6
	v_permlane32_swap_b32 v5, v7
	global_store_dwordx4 v[36:37], v[16:19], off
	global_store_dwordx4 v[36:37], v[20:23], off offset:32
	global_store_dwordx4 v[36:37], v[0:3], off offset:64
	global_store_dwordx4 v[36:37], v[4:7], off offset:96
	s_nop 1
	s_and_b64 s[46:47], s[0:1], exec
	s_cbranch_execnz .LBB0_1121
